# P10 main loop rewritten: member queries of each key block packed 4-per-tile across the whole workgroup (task list in LDS), partial sums added into LDS f32 accumulators under a 64-bit query lock
# speedup vs baseline: 1.0918x; 1.0454x over previous
.LBB0_1317:
	s_or_b64 exec, exec, s[0:1]
	s_bcnt1_i32_b64 s0, vcc
	s_waitcnt lgkmcnt(0)
	s_add_i32 s0, s8, s0
	v_ashrrev_i32_e32 v219, 31, v218
	v_ashrrev_i32_e32 v215, 31, v214
	s_lshl_b32 s1, s10, 21
	s_add_u32 s8, s36, s1
	s_addc_u32 s9, s37, 0
	s_add_u32 s11, s40, s1
	s_addc_u32 s12, s41, 0
	s_movk_i32 s82, 0x660
	s_waitcnt lgkmcnt(0)
	s_barrier
	v_lshlrev_b32_e32 v2, 4, v199
	v_mov_b32_e32 v22, v218
	v_mov_b32_e32 v23, v4
	v_mov_b32_e32 v24, v9
	v_mov_b32_e32 v25, v10
	v_and_b32_e32 v18, 7, v226
	v_lshlrev_b32_e32 v18, 3, v18
	v_mov_b32_e32 v19, 0x110
	v_mul_u32_u24_e32 v19, v19, v200
	v_lshl_add_u32 v19, v206, 2, v19
	v_add_u32_e32 v19, 0x4000, v19
	v_lshl_add_u32 v20, v216, 1, v210
	v_mov_b32_e32 v31, 0x110
	v_mul_u32_u24_e32 v31, v31, v200
	v_add_u32_e32 v31, 0x4100, v31
	v_add_u32_e32 v31, v31, v206
	v_mov_b32_e32 v82, 0
	v_mov_b32_e32 v83, 0
	v_mov_b32_e32 v84, 0
	v_mov_b32_e32 v85, 0
	s_lshl_b32 s0, s77, 10
	s_add_i32 s0, s0, 0x4000
	v_add_u32_e32 v28, s0, v2
	v_add_u32_e32 v29, 0x10000, v28
	ds_write_b128 v28, v[82:85]
	ds_write_b128 v28, v[82:85] offset:8192
	ds_write_b128 v28, v[82:85] offset:16384
	ds_write_b128 v28, v[82:85] offset:24576
	ds_write_b128 v28, v[82:85] offset:32768
	ds_write_b128 v28, v[82:85] offset:40960
	ds_write_b128 v28, v[82:85] offset:49152
	ds_write_b128 v28, v[82:85] offset:57344
	ds_write_b128 v29, v[82:85]
	ds_write_b128 v29, v[82:85] offset:8192
	ds_write_b128 v29, v[82:85] offset:16384
	ds_write_b128 v29, v[82:85] offset:24576
	ds_write_b128 v29, v[82:85] offset:32768
	v_mov_b32_e32 v86, 0x1800
	ds_write_b32 v86, v82
	ds_write_b64 v86, v[82:83] offset:8
	s_waitcnt lgkmcnt(0)
	s_barrier
	v_and_b32_e32 v102, 31, v199
	s_lshl_b32 s0, s77, 5
	v_add_u32_e32 v103, s0, v102
	s_mov_b64 s[58:59], exec
	v_cmp_gt_u32_e32 vcc, 32, v199
	s_and_b64 exec, exec, vcc
	v_lshlrev_b32_e32 v106, 3, v103
	ds_read_b64 v[104:105], v106
	s_waitcnt lgkmcnt(0)
	v_bcnt_u32_b32 v107, v104, 0
	v_bcnt_u32_b32 v107, v105, v107
	v_add_u32_e32 v108, 3, v107
	v_lshrrev_b32_e32 v108, 2, v108
	v_mov_b32_e32 v110, 0x1800
	ds_add_rtn_u32 v109, v110, v108
	s_waitcnt lgkmcnt(0)
.Lq_build:
	v_cmp_ne_u32_e32 vcc, 0, v107
	s_and_b64 exec, exec, vcc
	s_cbranch_execz .Lq_build_done
	v_mov_b32_e32 v118, 0
	v_mov_b32_e32 v119, 0
	v_ffbl_b32_e32 v111, v104
	v_ffbl_b32_e32 v112, v105
	v_add_u32_e32 v112, 32, v112
	v_cmp_ne_u32_e32 vcc, 0, v104
	v_cndmask_b32_e32 v111, v112, v111, vcc
	v_cmp_ne_u32_e64 s[14:15], 0, v107
	v_lshlrev_b32_e64 v113, v111, 1
	v_not_b32_e32 v113, v113
	v_cndmask_b32_e32 v114, -1, v113, vcc
	v_cndmask_b32_e64 v115, v113, -1, vcc
	v_and_b32_e32 v104, v104, v114
	v_and_b32_e32 v105, v105, v115
	v_lshlrev_b32_e32 v116, 0, v111
	v_cndmask_b32_e64 v116, 0, v116, s[14:15]
	v_or_b32_e32 v118, v118, v116
	v_cndmask_b32_e64 v117, 0, 1, s[14:15]
	v_add_u32_e32 v119, v119, v117
	v_sub_u32_e32 v107, v107, v117
	v_ffbl_b32_e32 v111, v104
	v_ffbl_b32_e32 v112, v105
	v_add_u32_e32 v112, 32, v112
	v_cmp_ne_u32_e32 vcc, 0, v104
	v_cndmask_b32_e32 v111, v112, v111, vcc
	v_cmp_ne_u32_e64 s[14:15], 0, v107
	v_lshlrev_b32_e64 v113, v111, 1
	v_not_b32_e32 v113, v113
	v_cndmask_b32_e32 v114, -1, v113, vcc
	v_cndmask_b32_e64 v115, v113, -1, vcc
	v_and_b32_e32 v104, v104, v114
	v_and_b32_e32 v105, v105, v115
	v_lshlrev_b32_e32 v116, 8, v111
	v_cndmask_b32_e64 v116, 0, v116, s[14:15]
	v_or_b32_e32 v118, v118, v116
	v_cndmask_b32_e64 v117, 0, 1, s[14:15]
	v_add_u32_e32 v119, v119, v117
	v_sub_u32_e32 v107, v107, v117
	v_ffbl_b32_e32 v111, v104
	v_ffbl_b32_e32 v112, v105
	v_add_u32_e32 v112, 32, v112
	v_cmp_ne_u32_e32 vcc, 0, v104
	v_cndmask_b32_e32 v111, v112, v111, vcc
	v_cmp_ne_u32_e64 s[14:15], 0, v107
	v_lshlrev_b32_e64 v113, v111, 1
	v_not_b32_e32 v113, v113
	v_cndmask_b32_e32 v114, -1, v113, vcc
	v_cndmask_b32_e64 v115, v113, -1, vcc
	v_and_b32_e32 v104, v104, v114
	v_and_b32_e32 v105, v105, v115
	v_lshlrev_b32_e32 v116, 16, v111
	v_cndmask_b32_e64 v116, 0, v116, s[14:15]
	v_or_b32_e32 v118, v118, v116
	v_cndmask_b32_e64 v117, 0, 1, s[14:15]
	v_add_u32_e32 v119, v119, v117
	v_sub_u32_e32 v107, v107, v117
	v_ffbl_b32_e32 v111, v104
	v_ffbl_b32_e32 v112, v105
	v_add_u32_e32 v112, 32, v112
	v_cmp_ne_u32_e32 vcc, 0, v104
	v_cndmask_b32_e32 v111, v112, v111, vcc
	v_cmp_ne_u32_e64 s[14:15], 0, v107
	v_lshlrev_b32_e64 v113, v111, 1
	v_not_b32_e32 v113, v113
	v_cndmask_b32_e32 v114, -1, v113, vcc
	v_cndmask_b32_e64 v115, v113, -1, vcc
	v_and_b32_e32 v104, v104, v114
	v_and_b32_e32 v105, v105, v115
	v_lshlrev_b32_e32 v116, 24, v111
	v_cndmask_b32_e64 v116, 0, v116, s[14:15]
	v_or_b32_e32 v118, v118, v116
	v_cndmask_b32_e64 v117, 0, 1, s[14:15]
	v_add_u32_e32 v119, v119, v117
	v_sub_u32_e32 v107, v107, v117
	v_lshl_or_b32 v120, v119, 8, v103
	v_mov_b32_e32 v121, v118
	v_lshlrev_b32_e32 v122, 3, v109
	ds_write_b64 v122, v[120:121] offset:2048
	v_add_u32_e32 v109, 1, v109
	s_branch .Lq_build
.Lq_build_done:
	s_mov_b64 exec, s[58:59]
	s_waitcnt lgkmcnt(0)
	s_barrier
	v_mov_b32_e32 v110, 0x1800
	ds_read_b32 v111, v110
	s_waitcnt lgkmcnt(0)
	v_readfirstlane_b32 s0, v111
	v_lshl_add_u32 v112, v199, 3, s77
	v_cmp_gt_u32_e32 vcc, s0, v112
	v_mov_b32_e32 v26, 0
	v_mov_b32_e32 v27, 0
	v_lshlrev_b32_e32 v113, 3, v112
	s_and_b64 exec, exec, vcc
	ds_read_b64 v[114:115], v113 offset:2048
	s_waitcnt lgkmcnt(0)
	v_mov_b32_e32 v26, v114
	v_mov_b32_e32 v27, v115
	s_mov_b64 exec, s[58:59]
	s_bcnt1_i32_b64 s10, vcc
	s_mov_b32 s52, 0
	s_mov_b32 s69, 0
	s_lshr_b32 s15, s69, 1
	s_min_u32 s14, s15, 63
	s_nop 3
	v_readlane_b32 s30, v26, s14
	v_readlane_b32 s31, v27, s14
	s_and_b32 s30, s30, 0xff
	s_lshl_b32 s30, s30, 13
	s_and_b32 s31, s69, 1
	s_lshl_b32 s31, s31, 12
	s_or_b32 s30, s30, s31
	s_add_u32 s64, s11, s30
	s_addc_u32 s65, s12, 0
	s_add_u32 s66, s8, s30
	s_addc_u32 s67, s9, 0
	global_load_dwordx4 v[178:181], v2, s[64:65]
	global_load_dwordx4 v[174:177], v2, s[64:65] offset:1024
	global_load_dwordx4 v[170:173], v2, s[64:65] offset:2048
	global_load_dwordx4 v[166:169], v2, s[64:65] offset:3072
	global_load_dwordx4 v[146:149], v2, s[66:67]
	global_load_dwordx4 v[142:145], v2, s[66:67] offset:1024
	global_load_dwordx4 v[126:129], v2, s[66:67] offset:2048
	global_load_dwordx4 v[114:117], v2, s[66:67] offset:3072
	s_mov_b32 s69, 0
	s_min_u32 s14, s69, 63
	s_nop 3
	v_readlane_b32 s30, v26, s14
	v_readlane_b32 s31, v27, s14
	v_bfe_u32 v28, s31, v18, 8
	v_lshl_add_u32 v29, s99, 6, v28
	v_mad_u32_u24 v29, v29, s47, v20
	global_load_dwordx4 v[238:241], v29, s[20:21]
	global_load_dwordx4 v[242:245], v29, s[20:21] offset:32
	global_load_dwordx4 v[246:249], v29, s[20:21] offset:64
	global_load_dwordx4 v[250:253], v29, s[20:21] offset:96
	s_mov_b32 s69, 1
	s_lshr_b32 s15, s69, 1
	s_min_u32 s14, s15, 63
	s_nop 3
	v_readlane_b32 s30, v26, s14
	v_readlane_b32 s31, v27, s14
	s_and_b32 s30, s30, 0xff
	s_lshl_b32 s30, s30, 13
	s_and_b32 s31, s69, 1
	s_lshl_b32 s31, s31, 12
	s_or_b32 s30, s30, s31
	s_add_u32 s64, s11, s30
	s_addc_u32 s65, s12, 0
	s_add_u32 s66, s8, s30
	s_addc_u32 s67, s9, 0
	global_load_dwordx4 v[162:165], v2, s[64:65]
	global_load_dwordx4 v[154:157], v2, s[64:65] offset:1024
	global_load_dwordx4 v[150:153], v2, s[64:65] offset:2048
	global_load_dwordx4 v[158:161], v2, s[64:65] offset:3072
	global_load_dwordx4 v[138:141], v2, s[66:67]
	global_load_dwordx4 v[122:125], v2, s[66:67] offset:1024
	global_load_dwordx4 v[110:113], v2, s[66:67] offset:2048
	global_load_dwordx4 v[106:109], v2, s[66:67] offset:3072
	s_mov_b32 s69, 2
	s_lshr_b32 s15, s69, 1
	s_min_u32 s14, s15, 63
	s_nop 3
	v_readlane_b32 s30, v26, s14
	v_readlane_b32 s31, v27, s14
	s_and_b32 s30, s30, 0xff
	s_lshl_b32 s30, s30, 13
	s_and_b32 s31, s69, 1
	s_lshl_b32 s31, s31, 12
	s_or_b32 s30, s30, s31
	s_add_u32 s64, s11, s30
	s_addc_u32 s65, s12, 0
	s_add_u32 s66, s8, s30
	s_addc_u32 s67, s9, 0
	global_load_dwordx4 v[194:197], v2, s[64:65]
	global_load_dwordx4 v[190:193], v2, s[64:65] offset:1024
	global_load_dwordx4 v[186:189], v2, s[64:65] offset:2048
	global_load_dwordx4 v[182:185], v2, s[64:65] offset:3072
	global_load_dwordx4 v[134:137], v2, s[66:67]
	global_load_dwordx4 v[130:133], v2, s[66:67] offset:1024
	global_load_dwordx4 v[118:121], v2, s[66:67] offset:2048
	global_load_dwordx4 v[102:105], v2, s[66:67] offset:3072
.Lq_loop:
.Lq_task_k0:
	s_lshr_b32 s68, s52, 1
	s_add_i32 s68, s68, 0
	s_cmp_ge_u32 s68, s10
	s_cbranch_scc1 .Lq_loop_end
	s_min_u32 s14, s68, 63
	s_nop 3
	v_readlane_b32 s56, v26, s14
	v_readlane_b32 s57, v27, s14
	s_and_b32 s100, s56, 0xff
	s_lshr_b32 s0, s56, 8
	s_lshl_b32 s18, 1, s0
	s_add_i32 s18, s18, -1
	s_waitcnt vmcnt(16)
	v_mov_b32_e32 v4, v238
	v_mov_b32_e32 v5, v239
	v_mov_b32_e32 v6, v240
	v_mov_b32_e32 v7, v241
	v_mov_b32_e32 v8, v242
	v_mov_b32_e32 v9, v243
	v_mov_b32_e32 v10, v244
	v_mov_b32_e32 v11, v245
	v_mov_b32_e32 v12, v246
	v_mov_b32_e32 v13, v247
	v_mov_b32_e32 v14, v248
	v_mov_b32_e32 v15, v249
	v_mov_b32_e32 v98, v250
	v_mov_b32_e32 v99, v251
	v_mov_b32_e32 v100, v252
	v_mov_b32_e32 v101, v253
	v_bfe_u32 v28, s57, v18, 8
	v_lshl_add_u32 v218, s99, 6, v28
	v_mad_u32_u24 v21, v28, s82, v19
	v_mad_u32_u24 v32, v28, s82, v31
	v_and_b32_e32 v29, s18, v230
	v_cmp_ne_u32_e64 s[54:55], 0, v29
	s_and_b64 s[54:55], s[54:55], s[6:7]
	s_add_i32 s69, s68, 1
	s_min_u32 s14, s69, 63
	s_nop 3
	v_readlane_b32 s30, v26, s14
	v_readlane_b32 s31, v27, s14
	v_bfe_u32 v28, s31, v18, 8
	v_lshl_add_u32 v29, s99, 6, v28
	v_mad_u32_u24 v29, v29, s47, v20
	global_load_dwordx4 v[238:241], v29, s[20:21]
	global_load_dwordx4 v[242:245], v29, s[20:21] offset:32
	global_load_dwordx4 v[246:249], v29, s[20:21] offset:64
	global_load_dwordx4 v[250:253], v29, s[20:21] offset:96
	s_lshl_b32 s0, s100, 6
	v_or_b32_e32 v237, s0, v206
	v_mov_b32_e32 v221, 0
	s_cmp_lg_u32 s100, s99
	s_cbranch_scc1 .Lq_s0n_k0
	v_and_b32_e32 v82, s18, v230
	v_cmp_ne_u32_e32 vcc, 0, v82
	s_and_b64 vcc, s[6:7], vcc
	v_mov_b32 v83, 0
	v_or_b32_e32 v16, 2, v237
	v_cndmask_b32_e32 v82, v236, v222, vcc
	v_sub_f32_e32 v82, v83, v82
	v_mov_b32_e32 v83, v82
	v_mov_b32_e32 v84, v82
	v_mov_b32_e32 v85, v82
	v_mov_b32_e32 v86, v82
	v_mov_b32_e32 v87, v82
	v_mov_b32_e32 v88, v82
	v_mov_b32_e32 v89, v82
	v_mov_b32_e32 v90, v82
	v_mov_b32_e32 v91, v82
	v_mov_b32_e32 v92, v82
	v_mov_b32_e32 v93, v82
	v_mov_b32_e32 v94, v82
	v_mov_b32_e32 v95, v82
	v_mov_b32_e32 v96, v82
	v_mov_b32_e32 v97, v82
	v_cmp_le_i32_e32 vcc, v237, v218
	v_or_b32_e32 v17, 3, v237
	v_mfma_f32_32x32x16_bf16 v[82:97], v[178:181], v[4:7], v[82:97]
	v_or_b32_e32 v30, 8, v237
	v_mfma_f32_32x32x16_bf16 v[82:97], v[174:177], v[8:11], v[82:97]
	v_mfma_f32_32x32x16_bf16 v[82:97], v[170:173], v[12:15], v[82:97]
	v_mfma_f32_32x32x16_bf16 v[82:97], v[166:169], v[98:101], v[82:97]
	s_nop 11
	v_exp_f32_e32 v82, v82
	v_exp_f32_e32 v83, v83
	v_exp_f32_e32 v84, v84
	v_exp_f32_e32 v85, v85
	v_exp_f32_e32 v86, v86
	v_cndmask_b32_e32 v82, 0, v82, vcc
	v_cmp_lt_i32_e32 vcc, v237, v218
	v_exp_f32_e32 v87, v87
	v_exp_f32_e32 v88, v88
	v_cndmask_b32_e32 v83, 0, v83, vcc
	v_cmp_le_i32_e32 vcc, v16, v218
	v_or_b32_e32 v16, 9, v237
	v_exp_f32_e32 v89, v89
	v_cndmask_b32_e32 v84, 0, v84, vcc
	v_cmp_le_i32_e32 vcc, v17, v218
	v_exp_f32_e32 v90, v90
	v_exp_f32_e32 v91, v91
	v_cndmask_b32_e32 v85, 0, v85, vcc
	v_cmp_le_i32_e32 vcc, v30, v218
	v_add_f32_e32 v221, v221, v82
	v_exp_f32_e32 v92, v92
	v_cndmask_b32_e32 v86, 0, v86, vcc
	v_cmp_le_i32_e32 vcc, v16, v218
	v_or_b32_e32 v16, 10, v237
	v_add_f32_e32 v221, v83, v221
	v_cndmask_b32_e32 v87, 0, v87, vcc
	v_cmp_le_i32_e32 vcc, v16, v218
	v_or_b32_e32 v16, 11, v237
	v_exp_f32_e32 v93, v93
	v_cndmask_b32_e32 v88, 0, v88, vcc
	v_cmp_le_i32_e32 vcc, v16, v218
	v_or_b32_e32 v16, 16, v237
	v_add_f32_e32 v221, v84, v221
	v_cndmask_b32_e32 v89, 0, v89, vcc
	v_cmp_le_i32_e32 vcc, v16, v218
	v_or_b32_e32 v16, 17, v237
	v_exp_f32_e32 v94, v94
	v_cndmask_b32_e32 v90, 0, v90, vcc
	v_cmp_le_i32_e32 vcc, v16, v218
	v_or_b32_e32 v16, 18, v237
	v_add_f32_e32 v221, v85, v221
	v_cndmask_b32_e32 v91, 0, v91, vcc
	v_cmp_le_i32_e32 vcc, v16, v218
	v_or_b32_e32 v16, 19, v237
	v_exp_f32_e32 v95, v95
	v_add_f32_e32 v221, v86, v221
	v_cndmask_b32_e32 v92, 0, v92, vcc
	v_cmp_le_i32_e32 vcc, v16, v218
	v_or_b32_e32 v16, 24, v237
	v_cvt_pk_bf16_f32 v82, v82, v83
	v_cvt_pk_bf16_f32 v83, v84, v85
	v_cvt_pk_bf16_f32 v84, v86, v87
	v_cvt_pk_bf16_f32 v85, v88, v89
	v_add_f32_e32 v221, v87, v221
	v_cndmask_b32_e32 v93, 0, v93, vcc
	v_cmp_le_i32_e32 vcc, v16, v218
	v_or_b32_e32 v16, 25, v237
	v_mfma_f32_32x32x16_bf16 v[66:81], v[146:149], v[82:85], 0
	v_add_f32_e32 v221, v88, v221
	v_cndmask_b32_e32 v94, 0, v94, vcc
	v_exp_f32_e32 v86, v96
	v_cmp_le_i32_e32 vcc, v16, v218
	v_or_b32_e32 v88, 26, v237
	v_add_f32_e32 v221, v89, v221
	v_cndmask_b32_e32 v87, 0, v95, vcc
	v_mfma_f32_32x32x16_bf16 v[50:65], v[142:145], v[82:85], 0
	v_cmp_le_i32_e32 vcc, v88, v218
	v_exp_f32_e32 v88, v97
	v_or_b32_e32 v82, 27, v237
	v_cndmask_b32_e32 v86, 0, v86, vcc
	v_cmp_le_i32_e32 vcc, v82, v218
	v_cvt_pk_bf16_f32 v82, v90, v91
	v_cvt_pk_bf16_f32 v83, v92, v93
	v_cndmask_b32_e32 v88, 0, v88, vcc
	v_cvt_pk_bf16_f32 v84, v94, v87
	v_cvt_pk_bf16_f32 v85, v86, v88
	v_add_f32_e32 v221, v90, v221
	v_add_f32_e32 v89, v91, v221
	v_mfma_f32_32x32x16_bf16 v[66:81], v[126:129], v[82:85], v[66:81]
	v_add_f32_e32 v89, v92, v89
	v_add_f32_e32 v89, v93, v89
	v_add_f32_e32 v89, v94, v89
	v_add_f32_e32 v87, v87, v89
	v_add_f32_e32 v86, v86, v87
	v_add_f32_e32 v221, v88, v86
	v_mfma_f32_32x32x16_bf16 v[50:65], v[114:117], v[82:85], v[50:65]
	s_branch .Lq_s0d_k0
.Lq_s0n_k0:
	v_and_b32_e32 v82, s18, v230
	v_cmp_ne_u32_e32 vcc, 0, v82
	s_and_b64 vcc, s[6:7], vcc
	v_mov_b32 v83, 0
	v_cndmask_b32_e32 v82, v236, v222, vcc
	v_sub_f32_e32 v82, v83, v82
	v_mov_b32_e32 v83, v82
	v_mov_b32_e32 v84, v82
	v_mov_b32_e32 v85, v82
	v_mov_b32_e32 v86, v82
	v_mov_b32_e32 v87, v82
	v_mov_b32_e32 v88, v82
	v_mov_b32_e32 v89, v82
	v_mov_b32_e32 v90, v82
	v_mov_b32_e32 v91, v82
	v_mov_b32_e32 v92, v82
	v_mov_b32_e32 v93, v82
	v_mov_b32_e32 v94, v82
	v_mov_b32_e32 v95, v82
	v_mov_b32_e32 v96, v82
	v_mov_b32_e32 v97, v82
	s_nop 0
	s_nop 0
	v_mfma_f32_32x32x16_bf16 v[82:97], v[178:181], v[4:7], v[82:97]
	v_mfma_f32_32x32x16_bf16 v[82:97], v[174:177], v[8:11], v[82:97]
	v_mfma_f32_32x32x16_bf16 v[82:97], v[170:173], v[12:15], v[82:97]
	v_mfma_f32_32x32x16_bf16 v[82:97], v[166:169], v[98:101], v[82:97]
	s_nop 11
	v_exp_f32_e32 v82, v82
	v_exp_f32_e32 v83, v83
	v_exp_f32_e32 v84, v84
	v_exp_f32_e32 v85, v85
	v_exp_f32_e32 v86, v86
	v_exp_f32_e32 v87, v87
	v_exp_f32_e32 v88, v88
	v_exp_f32_e32 v89, v89
	v_exp_f32_e32 v90, v90
	v_exp_f32_e32 v91, v91
	v_add_f32_e32 v221, v221, v82
	v_exp_f32_e32 v92, v92
	v_add_f32_e32 v221, v83, v221
	v_exp_f32_e32 v93, v93
	v_add_f32_e32 v221, v84, v221
	v_exp_f32_e32 v94, v94
	v_add_f32_e32 v221, v85, v221
	v_exp_f32_e32 v95, v95
	v_add_f32_e32 v221, v86, v221
	v_cvt_pk_bf16_f32 v82, v82, v83
	v_cvt_pk_bf16_f32 v83, v84, v85
	v_cvt_pk_bf16_f32 v84, v86, v87
	v_cvt_pk_bf16_f32 v85, v88, v89
	v_add_f32_e32 v221, v87, v221
	s_nop 0
	v_mfma_f32_32x32x16_bf16 v[66:81], v[146:149], v[82:85], 0
	v_add_f32_e32 v221, v88, v221
	v_exp_f32_e32 v86, v96
	v_add_f32_e32 v221, v89, v221
	v_mov_b32_e32 v87, v95
	v_mfma_f32_32x32x16_bf16 v[50:65], v[142:145], v[82:85], 0
	v_exp_f32_e32 v88, v97
	v_cvt_pk_bf16_f32 v82, v90, v91
	v_cvt_pk_bf16_f32 v83, v92, v93
	v_cvt_pk_bf16_f32 v84, v94, v87
	v_cvt_pk_bf16_f32 v85, v86, v88
	v_add_f32_e32 v221, v90, v221
	v_add_f32_e32 v89, v91, v221
	v_mfma_f32_32x32x16_bf16 v[66:81], v[126:129], v[82:85], v[66:81]
	v_add_f32_e32 v89, v92, v89
	v_add_f32_e32 v89, v93, v89
	v_add_f32_e32 v89, v94, v89
	v_add_f32_e32 v87, v87, v89
	v_add_f32_e32 v86, v86, v87
	v_add_f32_e32 v221, v88, v86
	v_mfma_f32_32x32x16_bf16 v[50:65], v[114:117], v[82:85], v[50:65]
.Lq_s0d_k0:
	s_lshl_b32 s69, s68, 1
	s_add_i32 s69, s69, 3
	s_lshr_b32 s15, s69, 1
	s_min_u32 s14, s15, 63
	s_nop 3
	v_readlane_b32 s30, v26, s14
	v_readlane_b32 s31, v27, s14
	s_and_b32 s30, s30, 0xff
	s_lshl_b32 s30, s30, 13
	s_and_b32 s31, s69, 1
	s_lshl_b32 s31, s31, 12
	s_or_b32 s30, s30, s31
	s_add_u32 s64, s11, s30
	s_addc_u32 s65, s12, 0
	s_add_u32 s66, s8, s30
	s_addc_u32 s67, s9, 0
	global_load_dwordx4 v[178:181], v2, s[64:65]
	global_load_dwordx4 v[174:177], v2, s[64:65] offset:1024
	global_load_dwordx4 v[170:173], v2, s[64:65] offset:2048
	global_load_dwordx4 v[166:169], v2, s[64:65] offset:3072
	global_load_dwordx4 v[146:149], v2, s[66:67]
	global_load_dwordx4 v[142:145], v2, s[66:67] offset:1024
	global_load_dwordx4 v[126:129], v2, s[66:67] offset:2048
	global_load_dwordx4 v[114:117], v2, s[66:67] offset:3072
	s_waitcnt vmcnt(20)
	s_lshl_b32 s0, s100, 6
	s_or_b32 s0, s0, 32
	v_or_b32_e32 v237, s0, v206
	s_cmp_lg_u32 s100, s99
	s_cbranch_scc1 .Lq_s1n_k0
	v_and_b32_e32 v82, s18, v230
	v_cmp_ne_u32_e32 vcc, 0, v82
	s_and_b64 vcc, s[6:7], vcc
	v_mov_b32 v83, 0
	v_or_b32_e32 v16, 2, v237
	v_cndmask_b32_e32 v82, v236, v222, vcc
	v_sub_f32_e32 v82, v83, v82
	v_mov_b32_e32 v83, v82
	v_mov_b32_e32 v84, v82
	v_mov_b32_e32 v85, v82
	v_mov_b32_e32 v86, v82
	v_mov_b32_e32 v87, v82
	v_mov_b32_e32 v88, v82
	v_mov_b32_e32 v89, v82
	v_mov_b32_e32 v90, v82
	v_mov_b32_e32 v91, v82
	v_mov_b32_e32 v92, v82
	v_mov_b32_e32 v93, v82
	v_mov_b32_e32 v94, v82
	v_mov_b32_e32 v95, v82
	v_mov_b32_e32 v96, v82
	v_mov_b32_e32 v97, v82
	v_cmp_le_i32_e32 vcc, v237, v218
	v_or_b32_e32 v17, 3, v237
	v_mfma_f32_32x32x16_bf16 v[82:97], v[162:165], v[4:7], v[82:97]
	v_or_b32_e32 v30, 8, v237
	v_mfma_f32_32x32x16_bf16 v[82:97], v[154:157], v[8:11], v[82:97]
	v_mfma_f32_32x32x16_bf16 v[82:97], v[150:153], v[12:15], v[82:97]
	v_mfma_f32_32x32x16_bf16 v[82:97], v[158:161], v[98:101], v[82:97]
	s_nop 11
	v_exp_f32_e32 v82, v82
	v_exp_f32_e32 v83, v83
	v_exp_f32_e32 v84, v84
	v_exp_f32_e32 v85, v85
	v_exp_f32_e32 v86, v86
	v_cndmask_b32_e32 v82, 0, v82, vcc
	v_cmp_lt_i32_e32 vcc, v237, v218
	v_exp_f32_e32 v87, v87
	v_exp_f32_e32 v88, v88
	v_cndmask_b32_e32 v83, 0, v83, vcc
	v_cmp_le_i32_e32 vcc, v16, v218
	v_or_b32_e32 v16, 9, v237
	v_exp_f32_e32 v89, v89
	v_cndmask_b32_e32 v84, 0, v84, vcc
	v_cmp_le_i32_e32 vcc, v17, v218
	v_exp_f32_e32 v90, v90
	v_exp_f32_e32 v91, v91
	v_cndmask_b32_e32 v85, 0, v85, vcc
	v_cmp_le_i32_e32 vcc, v30, v218
	v_add_f32_e32 v221, v221, v82
	v_exp_f32_e32 v92, v92
	v_cndmask_b32_e32 v86, 0, v86, vcc
	v_cmp_le_i32_e32 vcc, v16, v218
	v_or_b32_e32 v16, 10, v237
	v_add_f32_e32 v221, v83, v221
	v_cndmask_b32_e32 v87, 0, v87, vcc
	v_cmp_le_i32_e32 vcc, v16, v218
	v_or_b32_e32 v16, 11, v237
	v_exp_f32_e32 v93, v93
	v_cndmask_b32_e32 v88, 0, v88, vcc
	v_cmp_le_i32_e32 vcc, v16, v218
	v_or_b32_e32 v16, 16, v237
	v_add_f32_e32 v221, v84, v221
	v_cndmask_b32_e32 v89, 0, v89, vcc
	v_cmp_le_i32_e32 vcc, v16, v218
	v_or_b32_e32 v16, 17, v237
	v_exp_f32_e32 v94, v94
	v_cndmask_b32_e32 v90, 0, v90, vcc
	v_cmp_le_i32_e32 vcc, v16, v218
	v_or_b32_e32 v16, 18, v237
	v_add_f32_e32 v221, v85, v221
	v_cndmask_b32_e32 v91, 0, v91, vcc
	v_cmp_le_i32_e32 vcc, v16, v218
	v_or_b32_e32 v16, 19, v237
	v_exp_f32_e32 v95, v95
	v_add_f32_e32 v221, v86, v221
	v_cndmask_b32_e32 v92, 0, v92, vcc
	v_cmp_le_i32_e32 vcc, v16, v218
	v_or_b32_e32 v16, 24, v237
	v_cvt_pk_bf16_f32 v82, v82, v83
	v_cvt_pk_bf16_f32 v83, v84, v85
	v_cvt_pk_bf16_f32 v84, v86, v87
	v_cvt_pk_bf16_f32 v85, v88, v89
	v_add_f32_e32 v221, v87, v221
	v_cndmask_b32_e32 v93, 0, v93, vcc
	v_cmp_le_i32_e32 vcc, v16, v218
	v_or_b32_e32 v16, 25, v237
	v_mfma_f32_32x32x16_bf16 v[66:81], v[138:141], v[82:85], v[66:81]
	v_add_f32_e32 v221, v88, v221
	v_cndmask_b32_e32 v94, 0, v94, vcc
	v_exp_f32_e32 v86, v96
	v_cmp_le_i32_e32 vcc, v16, v218
	v_or_b32_e32 v88, 26, v237
	v_add_f32_e32 v221, v89, v221
	v_cndmask_b32_e32 v87, 0, v95, vcc
	v_mfma_f32_32x32x16_bf16 v[50:65], v[122:125], v[82:85], v[50:65]
	v_cmp_le_i32_e32 vcc, v88, v218
	v_exp_f32_e32 v88, v97
	v_or_b32_e32 v82, 27, v237
	v_cndmask_b32_e32 v86, 0, v86, vcc
	v_cmp_le_i32_e32 vcc, v82, v218
	v_cvt_pk_bf16_f32 v82, v90, v91
	v_cvt_pk_bf16_f32 v83, v92, v93
	v_cndmask_b32_e32 v88, 0, v88, vcc
	v_cvt_pk_bf16_f32 v84, v94, v87
	v_cvt_pk_bf16_f32 v85, v86, v88
	v_add_f32_e32 v221, v90, v221
	v_add_f32_e32 v89, v91, v221
	v_mfma_f32_32x32x16_bf16 v[66:81], v[110:113], v[82:85], v[66:81]
	v_add_f32_e32 v89, v92, v89
	v_add_f32_e32 v89, v93, v89
	v_add_f32_e32 v89, v94, v89
	v_add_f32_e32 v87, v87, v89
	v_add_f32_e32 v86, v86, v87
	v_add_f32_e32 v221, v88, v86
	v_mfma_f32_32x32x16_bf16 v[50:65], v[106:109], v[82:85], v[50:65]
	s_branch .Lq_s1d_k0
.Lq_s1n_k0:
	v_and_b32_e32 v82, s18, v230
	v_cmp_ne_u32_e32 vcc, 0, v82
	s_and_b64 vcc, s[6:7], vcc
	v_mov_b32 v83, 0
	v_cndmask_b32_e32 v82, v236, v222, vcc
	v_sub_f32_e32 v82, v83, v82
	v_mov_b32_e32 v83, v82
	v_mov_b32_e32 v84, v82
	v_mov_b32_e32 v85, v82
	v_mov_b32_e32 v86, v82
	v_mov_b32_e32 v87, v82
	v_mov_b32_e32 v88, v82
	v_mov_b32_e32 v89, v82
	v_mov_b32_e32 v90, v82
	v_mov_b32_e32 v91, v82
	v_mov_b32_e32 v92, v82
	v_mov_b32_e32 v93, v82
	v_mov_b32_e32 v94, v82
	v_mov_b32_e32 v95, v82
	v_mov_b32_e32 v96, v82
	v_mov_b32_e32 v97, v82
	s_nop 0
	s_nop 0
	v_mfma_f32_32x32x16_bf16 v[82:97], v[162:165], v[4:7], v[82:97]
	v_mfma_f32_32x32x16_bf16 v[82:97], v[154:157], v[8:11], v[82:97]
	v_mfma_f32_32x32x16_bf16 v[82:97], v[150:153], v[12:15], v[82:97]
	v_mfma_f32_32x32x16_bf16 v[82:97], v[158:161], v[98:101], v[82:97]
	s_nop 11
	v_exp_f32_e32 v82, v82
	v_exp_f32_e32 v83, v83
	v_exp_f32_e32 v84, v84
	v_exp_f32_e32 v85, v85
	v_exp_f32_e32 v86, v86
	v_exp_f32_e32 v87, v87
	v_exp_f32_e32 v88, v88
	v_exp_f32_e32 v89, v89
	v_exp_f32_e32 v90, v90
	v_exp_f32_e32 v91, v91
	v_add_f32_e32 v221, v221, v82
	v_exp_f32_e32 v92, v92
	v_add_f32_e32 v221, v83, v221
	v_exp_f32_e32 v93, v93
	v_add_f32_e32 v221, v84, v221
	v_exp_f32_e32 v94, v94
	v_add_f32_e32 v221, v85, v221
	v_exp_f32_e32 v95, v95
	v_add_f32_e32 v221, v86, v221
	v_cvt_pk_bf16_f32 v82, v82, v83
	v_cvt_pk_bf16_f32 v83, v84, v85
	v_cvt_pk_bf16_f32 v84, v86, v87
	v_cvt_pk_bf16_f32 v85, v88, v89
	v_add_f32_e32 v221, v87, v221
	s_nop 0
	v_mfma_f32_32x32x16_bf16 v[66:81], v[138:141], v[82:85], v[66:81]
	v_add_f32_e32 v221, v88, v221
	v_exp_f32_e32 v86, v96
	v_add_f32_e32 v221, v89, v221
	v_mov_b32_e32 v87, v95
	v_mfma_f32_32x32x16_bf16 v[50:65], v[122:125], v[82:85], v[50:65]
	v_exp_f32_e32 v88, v97
	v_cvt_pk_bf16_f32 v82, v90, v91
	v_cvt_pk_bf16_f32 v83, v92, v93
	v_cvt_pk_bf16_f32 v84, v94, v87
	v_cvt_pk_bf16_f32 v85, v86, v88
	v_add_f32_e32 v221, v90, v221
	v_add_f32_e32 v89, v91, v221
	v_mfma_f32_32x32x16_bf16 v[66:81], v[110:113], v[82:85], v[66:81]
	v_add_f32_e32 v89, v92, v89
	v_add_f32_e32 v89, v93, v89
	v_add_f32_e32 v89, v94, v89
	v_add_f32_e32 v87, v87, v89
	v_add_f32_e32 v86, v86, v87
	v_add_f32_e32 v221, v88, v86
	v_mfma_f32_32x32x16_bf16 v[50:65], v[106:109], v[82:85], v[50:65]
.Lq_s1d_k0:
	s_lshl_b32 s69, s68, 1
	s_add_i32 s69, s69, 4
	s_lshr_b32 s15, s69, 1
	s_min_u32 s14, s15, 63
	s_nop 3
	v_readlane_b32 s30, v26, s14
	v_readlane_b32 s31, v27, s14
	s_and_b32 s30, s30, 0xff
	s_lshl_b32 s30, s30, 13
	s_and_b32 s31, s69, 1
	s_lshl_b32 s31, s31, 12
	s_or_b32 s30, s30, s31
	s_add_u32 s64, s11, s30
	s_addc_u32 s65, s12, 0
	s_add_u32 s66, s8, s30
	s_addc_u32 s67, s9, 0
	global_load_dwordx4 v[162:165], v2, s[64:65]
	global_load_dwordx4 v[154:157], v2, s[64:65] offset:1024
	global_load_dwordx4 v[150:153], v2, s[64:65] offset:2048
	global_load_dwordx4 v[158:161], v2, s[64:65] offset:3072
	global_load_dwordx4 v[138:141], v2, s[66:67]
	global_load_dwordx4 v[122:125], v2, s[66:67] offset:1024
	global_load_dwordx4 v[110:113], v2, s[66:67] offset:2048
	global_load_dwordx4 v[106:109], v2, s[66:67] offset:3072
	s_mov_b64 s[60:61], 0
	s_lshr_b32 s0, s56, 8
	s_cmp_gt_u32 s0, 0
	s_cbranch_scc0 .Lq_m0_k0
	s_bfe_u32 s1, s57, 0x80000
	s_bitset1_b64 s[60:61], s1
.Lq_m0_k0:
	s_cmp_gt_u32 s0, 1
	s_cbranch_scc0 .Lq_m1_k0
	s_bfe_u32 s1, s57, 0x80008
	s_bitset1_b64 s[60:61], s1
.Lq_m1_k0:
	s_cmp_gt_u32 s0, 2
	s_cbranch_scc0 .Lq_m2_k0
	s_bfe_u32 s1, s57, 0x80010
	s_bitset1_b64 s[60:61], s1
.Lq_m2_k0:
	s_cmp_gt_u32 s0, 3
	s_cbranch_scc0 .Lq_m3_k0
	s_bfe_u32 s1, s57, 0x80018
	s_bitset1_b64 s[60:61], s1
.Lq_m3_k0:
	s_mov_b64 s[58:59], exec
	v_mov_b32_e32 v33, 0x1808
.Lq_lock_k0:
	s_mov_b64 exec, 1
	v_mov_b32_e32 v16, s60
	v_mov_b32_e32 v17, s61
	ds_or_rtn_b64 v[28:29], v33, v[16:17]
	s_waitcnt lgkmcnt(0)
	v_readfirstlane_b32 s62, v28
	v_readfirstlane_b32 s63, v29
	s_and_b64 s[64:65], s[62:63], s[60:61]
	s_cmp_eq_u64 s[64:65], 0
	s_cbranch_scc1 .Lq_locked_k0
	s_andn2_b64 s[64:65], s[60:61], s[62:63]
	s_not_b64 s[64:65], s[64:65]
	v_mov_b32_e32 v16, s64
	v_mov_b32_e32 v17, s65
	ds_and_b64 v33, v[16:17]
	s_sleep 2
	s_branch .Lq_lock_k0
.Lq_locked_k0:
	s_mov_b64 exec, s[54:55]
	ds_read_b128 v[82:85], v21
	ds_read_b128 v[86:89], v21 offset:32
	ds_read_b128 v[90:93], v21 offset:64
	ds_read_b128 v[94:97], v21 offset:96
	ds_read_b128 v[34:37], v21 offset:128
	ds_read_b128 v[38:41], v21 offset:160
	ds_read_b128 v[42:45], v21 offset:192
	ds_read_b128 v[46:49], v21 offset:224
	ds_read_b32 v28, v32
	s_waitcnt lgkmcnt(0)
	v_add_f32_e32 v82, v82, v66
	v_add_f32_e32 v83, v83, v67
	v_add_f32_e32 v84, v84, v68
	v_add_f32_e32 v85, v85, v69
	v_add_f32_e32 v86, v86, v70
	v_add_f32_e32 v87, v87, v71
	v_add_f32_e32 v88, v88, v72
	v_add_f32_e32 v89, v89, v73
	v_add_f32_e32 v90, v90, v74
	v_add_f32_e32 v91, v91, v75
	v_add_f32_e32 v92, v92, v76
	v_add_f32_e32 v93, v93, v77
	v_add_f32_e32 v94, v94, v78
	v_add_f32_e32 v95, v95, v79
	v_add_f32_e32 v96, v96, v80
	v_add_f32_e32 v97, v97, v81
	v_add_f32_e32 v34, v34, v50
	v_add_f32_e32 v35, v35, v51
	v_add_f32_e32 v36, v36, v52
	v_add_f32_e32 v37, v37, v53
	v_add_f32_e32 v38, v38, v54
	v_add_f32_e32 v39, v39, v55
	v_add_f32_e32 v40, v40, v56
	v_add_f32_e32 v41, v41, v57
	v_add_f32_e32 v42, v42, v58
	v_add_f32_e32 v43, v43, v59
	v_add_f32_e32 v44, v44, v60
	v_add_f32_e32 v45, v45, v61
	v_add_f32_e32 v46, v46, v62
	v_add_f32_e32 v47, v47, v63
	v_add_f32_e32 v48, v48, v64
	v_add_f32_e32 v49, v49, v65
	v_add_f32_e32 v28, v28, v221
	ds_write_b128 v21, v[82:85]
	ds_write_b128 v21, v[86:89] offset:32
	ds_write_b128 v21, v[90:93] offset:64
	ds_write_b128 v21, v[94:97] offset:96
	ds_write_b128 v21, v[34:37] offset:128
	ds_write_b128 v21, v[38:41] offset:160
	ds_write_b128 v21, v[42:45] offset:192
	ds_write_b128 v21, v[46:49] offset:224
	ds_write_b32 v32, v28
	s_mov_b64 exec, 1
	s_not_b64 s[64:65], s[60:61]
	v_mov_b32_e32 v16, s64
	v_mov_b32_e32 v17, s65
	ds_and_b64 v33, v[16:17]
	s_mov_b64 exec, s[58:59]
.Lq_task_k1:
	s_lshr_b32 s68, s52, 1
	s_add_i32 s68, s68, 1
	s_cmp_ge_u32 s68, s10
	s_cbranch_scc1 .Lq_loop_end
	s_min_u32 s14, s68, 63
	s_nop 3
	v_readlane_b32 s56, v26, s14
	v_readlane_b32 s57, v27, s14
	s_and_b32 s100, s56, 0xff
	s_lshr_b32 s0, s56, 8
	s_lshl_b32 s18, 1, s0
	s_add_i32 s18, s18, -1
	s_waitcnt vmcnt(16)
	v_mov_b32_e32 v4, v238
	v_mov_b32_e32 v5, v239
	v_mov_b32_e32 v6, v240
	v_mov_b32_e32 v7, v241
	v_mov_b32_e32 v8, v242
	v_mov_b32_e32 v9, v243
	v_mov_b32_e32 v10, v244
	v_mov_b32_e32 v11, v245
	v_mov_b32_e32 v12, v246
	v_mov_b32_e32 v13, v247
	v_mov_b32_e32 v14, v248
	v_mov_b32_e32 v15, v249
	v_mov_b32_e32 v98, v250
	v_mov_b32_e32 v99, v251
	v_mov_b32_e32 v100, v252
	v_mov_b32_e32 v101, v253
	v_bfe_u32 v28, s57, v18, 8
	v_lshl_add_u32 v218, s99, 6, v28
	v_mad_u32_u24 v21, v28, s82, v19
	v_mad_u32_u24 v32, v28, s82, v31
	v_and_b32_e32 v29, s18, v230
	v_cmp_ne_u32_e64 s[54:55], 0, v29
	s_and_b64 s[54:55], s[54:55], s[6:7]
	s_add_i32 s69, s68, 1
	s_min_u32 s14, s69, 63
	s_nop 3
	v_readlane_b32 s30, v26, s14
	v_readlane_b32 s31, v27, s14
	v_bfe_u32 v28, s31, v18, 8
	v_lshl_add_u32 v29, s99, 6, v28
	v_mad_u32_u24 v29, v29, s47, v20
	global_load_dwordx4 v[238:241], v29, s[20:21]
	global_load_dwordx4 v[242:245], v29, s[20:21] offset:32
	global_load_dwordx4 v[246:249], v29, s[20:21] offset:64
	global_load_dwordx4 v[250:253], v29, s[20:21] offset:96
	s_lshl_b32 s0, s100, 6
	v_or_b32_e32 v237, s0, v206
	v_mov_b32_e32 v221, 0
	s_cmp_lg_u32 s100, s99
	s_cbranch_scc1 .Lq_s0n_k1
	v_and_b32_e32 v82, s18, v230
	v_cmp_ne_u32_e32 vcc, 0, v82
	s_and_b64 vcc, s[6:7], vcc
	v_mov_b32 v83, 0
	v_or_b32_e32 v16, 2, v237
	v_cndmask_b32_e32 v82, v236, v222, vcc
	v_sub_f32_e32 v82, v83, v82
	v_mov_b32_e32 v83, v82
	v_mov_b32_e32 v84, v82
	v_mov_b32_e32 v85, v82
	v_mov_b32_e32 v86, v82
	v_mov_b32_e32 v87, v82
	v_mov_b32_e32 v88, v82
	v_mov_b32_e32 v89, v82
	v_mov_b32_e32 v90, v82
	v_mov_b32_e32 v91, v82
	v_mov_b32_e32 v92, v82
	v_mov_b32_e32 v93, v82
	v_mov_b32_e32 v94, v82
	v_mov_b32_e32 v95, v82
	v_mov_b32_e32 v96, v82
	v_mov_b32_e32 v97, v82
	v_cmp_le_i32_e32 vcc, v237, v218
	v_or_b32_e32 v17, 3, v237
	v_mfma_f32_32x32x16_bf16 v[82:97], v[194:197], v[4:7], v[82:97]
	v_or_b32_e32 v30, 8, v237
	v_mfma_f32_32x32x16_bf16 v[82:97], v[190:193], v[8:11], v[82:97]
	v_mfma_f32_32x32x16_bf16 v[82:97], v[186:189], v[12:15], v[82:97]
	v_mfma_f32_32x32x16_bf16 v[82:97], v[182:185], v[98:101], v[82:97]
	s_nop 11
	v_exp_f32_e32 v82, v82
	v_exp_f32_e32 v83, v83
	v_exp_f32_e32 v84, v84
	v_exp_f32_e32 v85, v85
	v_exp_f32_e32 v86, v86
	v_cndmask_b32_e32 v82, 0, v82, vcc
	v_cmp_lt_i32_e32 vcc, v237, v218
	v_exp_f32_e32 v87, v87
	v_exp_f32_e32 v88, v88
	v_cndmask_b32_e32 v83, 0, v83, vcc
	v_cmp_le_i32_e32 vcc, v16, v218
	v_or_b32_e32 v16, 9, v237
	v_exp_f32_e32 v89, v89
	v_cndmask_b32_e32 v84, 0, v84, vcc
	v_cmp_le_i32_e32 vcc, v17, v218
	v_exp_f32_e32 v90, v90
	v_exp_f32_e32 v91, v91
	v_cndmask_b32_e32 v85, 0, v85, vcc
	v_cmp_le_i32_e32 vcc, v30, v218
	v_add_f32_e32 v221, v221, v82
	v_exp_f32_e32 v92, v92
	v_cndmask_b32_e32 v86, 0, v86, vcc
	v_cmp_le_i32_e32 vcc, v16, v218
	v_or_b32_e32 v16, 10, v237
	v_add_f32_e32 v221, v83, v221
	v_cndmask_b32_e32 v87, 0, v87, vcc
	v_cmp_le_i32_e32 vcc, v16, v218
	v_or_b32_e32 v16, 11, v237
	v_exp_f32_e32 v93, v93
	v_cndmask_b32_e32 v88, 0, v88, vcc
	v_cmp_le_i32_e32 vcc, v16, v218
	v_or_b32_e32 v16, 16, v237
	v_add_f32_e32 v221, v84, v221
	v_cndmask_b32_e32 v89, 0, v89, vcc
	v_cmp_le_i32_e32 vcc, v16, v218
	v_or_b32_e32 v16, 17, v237
	v_exp_f32_e32 v94, v94
	v_cndmask_b32_e32 v90, 0, v90, vcc
	v_cmp_le_i32_e32 vcc, v16, v218
	v_or_b32_e32 v16, 18, v237
	v_add_f32_e32 v221, v85, v221
	v_cndmask_b32_e32 v91, 0, v91, vcc
	v_cmp_le_i32_e32 vcc, v16, v218
	v_or_b32_e32 v16, 19, v237
	v_exp_f32_e32 v95, v95
	v_add_f32_e32 v221, v86, v221
	v_cndmask_b32_e32 v92, 0, v92, vcc
	v_cmp_le_i32_e32 vcc, v16, v218
	v_or_b32_e32 v16, 24, v237
	v_cvt_pk_bf16_f32 v82, v82, v83
	v_cvt_pk_bf16_f32 v83, v84, v85
	v_cvt_pk_bf16_f32 v84, v86, v87
	v_cvt_pk_bf16_f32 v85, v88, v89
	v_add_f32_e32 v221, v87, v221
	v_cndmask_b32_e32 v93, 0, v93, vcc
	v_cmp_le_i32_e32 vcc, v16, v218
	v_or_b32_e32 v16, 25, v237
	v_mfma_f32_32x32x16_bf16 v[66:81], v[134:137], v[82:85], 0
	v_add_f32_e32 v221, v88, v221
	v_cndmask_b32_e32 v94, 0, v94, vcc
	v_exp_f32_e32 v86, v96
	v_cmp_le_i32_e32 vcc, v16, v218
	v_or_b32_e32 v88, 26, v237
	v_add_f32_e32 v221, v89, v221
	v_cndmask_b32_e32 v87, 0, v95, vcc
	v_mfma_f32_32x32x16_bf16 v[50:65], v[130:133], v[82:85], 0
	v_cmp_le_i32_e32 vcc, v88, v218
	v_exp_f32_e32 v88, v97
	v_or_b32_e32 v82, 27, v237
	v_cndmask_b32_e32 v86, 0, v86, vcc
	v_cmp_le_i32_e32 vcc, v82, v218
	v_cvt_pk_bf16_f32 v82, v90, v91
	v_cvt_pk_bf16_f32 v83, v92, v93
	v_cndmask_b32_e32 v88, 0, v88, vcc
	v_cvt_pk_bf16_f32 v84, v94, v87
	v_cvt_pk_bf16_f32 v85, v86, v88
	v_add_f32_e32 v221, v90, v221
	v_add_f32_e32 v89, v91, v221
	v_mfma_f32_32x32x16_bf16 v[66:81], v[118:121], v[82:85], v[66:81]
	v_add_f32_e32 v89, v92, v89
	v_add_f32_e32 v89, v93, v89
	v_add_f32_e32 v89, v94, v89
	v_add_f32_e32 v87, v87, v89
	v_add_f32_e32 v86, v86, v87
	v_add_f32_e32 v221, v88, v86
	v_mfma_f32_32x32x16_bf16 v[50:65], v[102:105], v[82:85], v[50:65]
	s_branch .Lq_s0d_k1
.Lq_s0n_k1:
	v_and_b32_e32 v82, s18, v230
	v_cmp_ne_u32_e32 vcc, 0, v82
	s_and_b64 vcc, s[6:7], vcc
	v_mov_b32 v83, 0
	v_cndmask_b32_e32 v82, v236, v222, vcc
	v_sub_f32_e32 v82, v83, v82
	v_mov_b32_e32 v83, v82
	v_mov_b32_e32 v84, v82
	v_mov_b32_e32 v85, v82
	v_mov_b32_e32 v86, v82
	v_mov_b32_e32 v87, v82
	v_mov_b32_e32 v88, v82
	v_mov_b32_e32 v89, v82
	v_mov_b32_e32 v90, v82
	v_mov_b32_e32 v91, v82
	v_mov_b32_e32 v92, v82
	v_mov_b32_e32 v93, v82
	v_mov_b32_e32 v94, v82
	v_mov_b32_e32 v95, v82
	v_mov_b32_e32 v96, v82
	v_mov_b32_e32 v97, v82
	s_nop 0
	s_nop 0
	v_mfma_f32_32x32x16_bf16 v[82:97], v[194:197], v[4:7], v[82:97]
	v_mfma_f32_32x32x16_bf16 v[82:97], v[190:193], v[8:11], v[82:97]
	v_mfma_f32_32x32x16_bf16 v[82:97], v[186:189], v[12:15], v[82:97]
	v_mfma_f32_32x32x16_bf16 v[82:97], v[182:185], v[98:101], v[82:97]
	s_nop 11
	v_exp_f32_e32 v82, v82
	v_exp_f32_e32 v83, v83
	v_exp_f32_e32 v84, v84
	v_exp_f32_e32 v85, v85
	v_exp_f32_e32 v86, v86
	v_exp_f32_e32 v87, v87
	v_exp_f32_e32 v88, v88
	v_exp_f32_e32 v89, v89
	v_exp_f32_e32 v90, v90
	v_exp_f32_e32 v91, v91
	v_add_f32_e32 v221, v221, v82
	v_exp_f32_e32 v92, v92
	v_add_f32_e32 v221, v83, v221
	v_exp_f32_e32 v93, v93
	v_add_f32_e32 v221, v84, v221
	v_exp_f32_e32 v94, v94
	v_add_f32_e32 v221, v85, v221
	v_exp_f32_e32 v95, v95
	v_add_f32_e32 v221, v86, v221
	v_cvt_pk_bf16_f32 v82, v82, v83
	v_cvt_pk_bf16_f32 v83, v84, v85
	v_cvt_pk_bf16_f32 v84, v86, v87
	v_cvt_pk_bf16_f32 v85, v88, v89
	v_add_f32_e32 v221, v87, v221
	s_nop 0
	v_mfma_f32_32x32x16_bf16 v[66:81], v[134:137], v[82:85], 0
	v_add_f32_e32 v221, v88, v221
	v_exp_f32_e32 v86, v96
	v_add_f32_e32 v221, v89, v221
	v_mov_b32_e32 v87, v95
	v_mfma_f32_32x32x16_bf16 v[50:65], v[130:133], v[82:85], 0
	v_exp_f32_e32 v88, v97
	v_cvt_pk_bf16_f32 v82, v90, v91
	v_cvt_pk_bf16_f32 v83, v92, v93
	v_cvt_pk_bf16_f32 v84, v94, v87
	v_cvt_pk_bf16_f32 v85, v86, v88
	v_add_f32_e32 v221, v90, v221
	v_add_f32_e32 v89, v91, v221
	v_mfma_f32_32x32x16_bf16 v[66:81], v[118:121], v[82:85], v[66:81]
	v_add_f32_e32 v89, v92, v89
	v_add_f32_e32 v89, v93, v89
	v_add_f32_e32 v89, v94, v89
	v_add_f32_e32 v87, v87, v89
	v_add_f32_e32 v86, v86, v87
	v_add_f32_e32 v221, v88, v86
	v_mfma_f32_32x32x16_bf16 v[50:65], v[102:105], v[82:85], v[50:65]
.Lq_s0d_k1:
	s_lshl_b32 s69, s68, 1
	s_add_i32 s69, s69, 3
	s_lshr_b32 s15, s69, 1
	s_min_u32 s14, s15, 63
	s_nop 3
	v_readlane_b32 s30, v26, s14
	v_readlane_b32 s31, v27, s14
	s_and_b32 s30, s30, 0xff
	s_lshl_b32 s30, s30, 13
	s_and_b32 s31, s69, 1
	s_lshl_b32 s31, s31, 12
	s_or_b32 s30, s30, s31
	s_add_u32 s64, s11, s30
	s_addc_u32 s65, s12, 0
	s_add_u32 s66, s8, s30
	s_addc_u32 s67, s9, 0
	global_load_dwordx4 v[194:197], v2, s[64:65]
	global_load_dwordx4 v[190:193], v2, s[64:65] offset:1024
	global_load_dwordx4 v[186:189], v2, s[64:65] offset:2048
	global_load_dwordx4 v[182:185], v2, s[64:65] offset:3072
	global_load_dwordx4 v[134:137], v2, s[66:67]
	global_load_dwordx4 v[130:133], v2, s[66:67] offset:1024
	global_load_dwordx4 v[118:121], v2, s[66:67] offset:2048
	global_load_dwordx4 v[102:105], v2, s[66:67] offset:3072
	s_waitcnt vmcnt(20)
	s_lshl_b32 s0, s100, 6
	s_or_b32 s0, s0, 32
	v_or_b32_e32 v237, s0, v206
	s_cmp_lg_u32 s100, s99
	s_cbranch_scc1 .Lq_s1n_k1
	v_and_b32_e32 v82, s18, v230
	v_cmp_ne_u32_e32 vcc, 0, v82
	s_and_b64 vcc, s[6:7], vcc
	v_mov_b32 v83, 0
	v_or_b32_e32 v16, 2, v237
	v_cndmask_b32_e32 v82, v236, v222, vcc
	v_sub_f32_e32 v82, v83, v82
	v_mov_b32_e32 v83, v82
	v_mov_b32_e32 v84, v82
	v_mov_b32_e32 v85, v82
	v_mov_b32_e32 v86, v82
	v_mov_b32_e32 v87, v82
	v_mov_b32_e32 v88, v82
	v_mov_b32_e32 v89, v82
	v_mov_b32_e32 v90, v82
	v_mov_b32_e32 v91, v82
	v_mov_b32_e32 v92, v82
	v_mov_b32_e32 v93, v82
	v_mov_b32_e32 v94, v82
	v_mov_b32_e32 v95, v82
	v_mov_b32_e32 v96, v82
	v_mov_b32_e32 v97, v82
	v_cmp_le_i32_e32 vcc, v237, v218
	v_or_b32_e32 v17, 3, v237
	v_mfma_f32_32x32x16_bf16 v[82:97], v[178:181], v[4:7], v[82:97]
	v_or_b32_e32 v30, 8, v237
	v_mfma_f32_32x32x16_bf16 v[82:97], v[174:177], v[8:11], v[82:97]
	v_mfma_f32_32x32x16_bf16 v[82:97], v[170:173], v[12:15], v[82:97]
	v_mfma_f32_32x32x16_bf16 v[82:97], v[166:169], v[98:101], v[82:97]
	s_nop 11
	v_exp_f32_e32 v82, v82
	v_exp_f32_e32 v83, v83
	v_exp_f32_e32 v84, v84
	v_exp_f32_e32 v85, v85
	v_exp_f32_e32 v86, v86
	v_cndmask_b32_e32 v82, 0, v82, vcc
	v_cmp_lt_i32_e32 vcc, v237, v218
	v_exp_f32_e32 v87, v87
	v_exp_f32_e32 v88, v88
	v_cndmask_b32_e32 v83, 0, v83, vcc
	v_cmp_le_i32_e32 vcc, v16, v218
	v_or_b32_e32 v16, 9, v237
	v_exp_f32_e32 v89, v89
	v_cndmask_b32_e32 v84, 0, v84, vcc
	v_cmp_le_i32_e32 vcc, v17, v218
	v_exp_f32_e32 v90, v90
	v_exp_f32_e32 v91, v91
	v_cndmask_b32_e32 v85, 0, v85, vcc
	v_cmp_le_i32_e32 vcc, v30, v218
	v_add_f32_e32 v221, v221, v82
	v_exp_f32_e32 v92, v92
	v_cndmask_b32_e32 v86, 0, v86, vcc
	v_cmp_le_i32_e32 vcc, v16, v218
	v_or_b32_e32 v16, 10, v237
	v_add_f32_e32 v221, v83, v221
	v_cndmask_b32_e32 v87, 0, v87, vcc
	v_cmp_le_i32_e32 vcc, v16, v218
	v_or_b32_e32 v16, 11, v237
	v_exp_f32_e32 v93, v93
	v_cndmask_b32_e32 v88, 0, v88, vcc
	v_cmp_le_i32_e32 vcc, v16, v218
	v_or_b32_e32 v16, 16, v237
	v_add_f32_e32 v221, v84, v221
	v_cndmask_b32_e32 v89, 0, v89, vcc
	v_cmp_le_i32_e32 vcc, v16, v218
	v_or_b32_e32 v16, 17, v237
	v_exp_f32_e32 v94, v94
	v_cndmask_b32_e32 v90, 0, v90, vcc
	v_cmp_le_i32_e32 vcc, v16, v218
	v_or_b32_e32 v16, 18, v237
	v_add_f32_e32 v221, v85, v221
	v_cndmask_b32_e32 v91, 0, v91, vcc
	v_cmp_le_i32_e32 vcc, v16, v218
	v_or_b32_e32 v16, 19, v237
	v_exp_f32_e32 v95, v95
	v_add_f32_e32 v221, v86, v221
	v_cndmask_b32_e32 v92, 0, v92, vcc
	v_cmp_le_i32_e32 vcc, v16, v218
	v_or_b32_e32 v16, 24, v237
	v_cvt_pk_bf16_f32 v82, v82, v83
	v_cvt_pk_bf16_f32 v83, v84, v85
	v_cvt_pk_bf16_f32 v84, v86, v87
	v_cvt_pk_bf16_f32 v85, v88, v89
	v_add_f32_e32 v221, v87, v221
	v_cndmask_b32_e32 v93, 0, v93, vcc
	v_cmp_le_i32_e32 vcc, v16, v218
	v_or_b32_e32 v16, 25, v237
	v_mfma_f32_32x32x16_bf16 v[66:81], v[146:149], v[82:85], v[66:81]
	v_add_f32_e32 v221, v88, v221
	v_cndmask_b32_e32 v94, 0, v94, vcc
	v_exp_f32_e32 v86, v96
	v_cmp_le_i32_e32 vcc, v16, v218
	v_or_b32_e32 v88, 26, v237
	v_add_f32_e32 v221, v89, v221
	v_cndmask_b32_e32 v87, 0, v95, vcc
	v_mfma_f32_32x32x16_bf16 v[50:65], v[142:145], v[82:85], v[50:65]
	v_cmp_le_i32_e32 vcc, v88, v218
	v_exp_f32_e32 v88, v97
	v_or_b32_e32 v82, 27, v237
	v_cndmask_b32_e32 v86, 0, v86, vcc
	v_cmp_le_i32_e32 vcc, v82, v218
	v_cvt_pk_bf16_f32 v82, v90, v91
	v_cvt_pk_bf16_f32 v83, v92, v93
	v_cndmask_b32_e32 v88, 0, v88, vcc
	v_cvt_pk_bf16_f32 v84, v94, v87
	v_cvt_pk_bf16_f32 v85, v86, v88
	v_add_f32_e32 v221, v90, v221
	v_add_f32_e32 v89, v91, v221
	v_mfma_f32_32x32x16_bf16 v[66:81], v[126:129], v[82:85], v[66:81]
	v_add_f32_e32 v89, v92, v89
	v_add_f32_e32 v89, v93, v89
	v_add_f32_e32 v89, v94, v89
	v_add_f32_e32 v87, v87, v89
	v_add_f32_e32 v86, v86, v87
	v_add_f32_e32 v221, v88, v86
	v_mfma_f32_32x32x16_bf16 v[50:65], v[114:117], v[82:85], v[50:65]
	s_branch .Lq_s1d_k1
.Lq_s1n_k1:
	v_and_b32_e32 v82, s18, v230
	v_cmp_ne_u32_e32 vcc, 0, v82
	s_and_b64 vcc, s[6:7], vcc
	v_mov_b32 v83, 0
	v_cndmask_b32_e32 v82, v236, v222, vcc
	v_sub_f32_e32 v82, v83, v82
	v_mov_b32_e32 v83, v82
	v_mov_b32_e32 v84, v82
	v_mov_b32_e32 v85, v82
	v_mov_b32_e32 v86, v82
	v_mov_b32_e32 v87, v82
	v_mov_b32_e32 v88, v82
	v_mov_b32_e32 v89, v82
	v_mov_b32_e32 v90, v82
	v_mov_b32_e32 v91, v82
	v_mov_b32_e32 v92, v82
	v_mov_b32_e32 v93, v82
	v_mov_b32_e32 v94, v82
	v_mov_b32_e32 v95, v82
	v_mov_b32_e32 v96, v82
	v_mov_b32_e32 v97, v82
	s_nop 0
	s_nop 0
	v_mfma_f32_32x32x16_bf16 v[82:97], v[178:181], v[4:7], v[82:97]
	v_mfma_f32_32x32x16_bf16 v[82:97], v[174:177], v[8:11], v[82:97]
	v_mfma_f32_32x32x16_bf16 v[82:97], v[170:173], v[12:15], v[82:97]
	v_mfma_f32_32x32x16_bf16 v[82:97], v[166:169], v[98:101], v[82:97]
	s_nop 11
	v_exp_f32_e32 v82, v82
	v_exp_f32_e32 v83, v83
	v_exp_f32_e32 v84, v84
	v_exp_f32_e32 v85, v85
	v_exp_f32_e32 v86, v86
	v_exp_f32_e32 v87, v87
	v_exp_f32_e32 v88, v88
	v_exp_f32_e32 v89, v89
	v_exp_f32_e32 v90, v90
	v_exp_f32_e32 v91, v91
	v_add_f32_e32 v221, v221, v82
	v_exp_f32_e32 v92, v92
	v_add_f32_e32 v221, v83, v221
	v_exp_f32_e32 v93, v93
	v_add_f32_e32 v221, v84, v221
	v_exp_f32_e32 v94, v94
	v_add_f32_e32 v221, v85, v221
	v_exp_f32_e32 v95, v95
	v_add_f32_e32 v221, v86, v221
	v_cvt_pk_bf16_f32 v82, v82, v83
	v_cvt_pk_bf16_f32 v83, v84, v85
	v_cvt_pk_bf16_f32 v84, v86, v87
	v_cvt_pk_bf16_f32 v85, v88, v89
	v_add_f32_e32 v221, v87, v221
	s_nop 0
	v_mfma_f32_32x32x16_bf16 v[66:81], v[146:149], v[82:85], v[66:81]
	v_add_f32_e32 v221, v88, v221
	v_exp_f32_e32 v86, v96
	v_add_f32_e32 v221, v89, v221
	v_mov_b32_e32 v87, v95
	v_mfma_f32_32x32x16_bf16 v[50:65], v[142:145], v[82:85], v[50:65]
	v_exp_f32_e32 v88, v97
	v_cvt_pk_bf16_f32 v82, v90, v91
	v_cvt_pk_bf16_f32 v83, v92, v93
	v_cvt_pk_bf16_f32 v84, v94, v87
	v_cvt_pk_bf16_f32 v85, v86, v88
	v_add_f32_e32 v221, v90, v221
	v_add_f32_e32 v89, v91, v221
	v_mfma_f32_32x32x16_bf16 v[66:81], v[126:129], v[82:85], v[66:81]
	v_add_f32_e32 v89, v92, v89
	v_add_f32_e32 v89, v93, v89
	v_add_f32_e32 v89, v94, v89
	v_add_f32_e32 v87, v87, v89
	v_add_f32_e32 v86, v86, v87
	v_add_f32_e32 v221, v88, v86
	v_mfma_f32_32x32x16_bf16 v[50:65], v[114:117], v[82:85], v[50:65]
.Lq_s1d_k1:
	s_lshl_b32 s69, s68, 1
	s_add_i32 s69, s69, 4
	s_lshr_b32 s15, s69, 1
	s_min_u32 s14, s15, 63
	s_nop 3
	v_readlane_b32 s30, v26, s14
	v_readlane_b32 s31, v27, s14
	s_and_b32 s30, s30, 0xff
	s_lshl_b32 s30, s30, 13
	s_and_b32 s31, s69, 1
	s_lshl_b32 s31, s31, 12
	s_or_b32 s30, s30, s31
	s_add_u32 s64, s11, s30
	s_addc_u32 s65, s12, 0
	s_add_u32 s66, s8, s30
	s_addc_u32 s67, s9, 0
	global_load_dwordx4 v[178:181], v2, s[64:65]
	global_load_dwordx4 v[174:177], v2, s[64:65] offset:1024
	global_load_dwordx4 v[170:173], v2, s[64:65] offset:2048
	global_load_dwordx4 v[166:169], v2, s[64:65] offset:3072
	global_load_dwordx4 v[146:149], v2, s[66:67]
	global_load_dwordx4 v[142:145], v2, s[66:67] offset:1024
	global_load_dwordx4 v[126:129], v2, s[66:67] offset:2048
	global_load_dwordx4 v[114:117], v2, s[66:67] offset:3072
	s_mov_b64 s[60:61], 0
	s_lshr_b32 s0, s56, 8
	s_cmp_gt_u32 s0, 0
	s_cbranch_scc0 .Lq_m0_k1
	s_bfe_u32 s1, s57, 0x80000
	s_bitset1_b64 s[60:61], s1

.Lq_task_k2:
	s_lshr_b32 s68, s52, 1
	s_add_i32 s68, s68, 2
	s_cmp_ge_u32 s68, s10
	s_cbranch_scc1 .Lq_loop_end
	s_min_u32 s14, s68, 63
	s_nop 3
	v_readlane_b32 s56, v26, s14
	v_readlane_b32 s57, v27, s14
	s_and_b32 s100, s56, 0xff
	s_lshr_b32 s0, s56, 8
	s_lshl_b32 s18, 1, s0
	s_add_i32 s18, s18, -1
	s_waitcnt vmcnt(16)
	v_mov_b32_e32 v4, v238
	v_mov_b32_e32 v5, v239
	v_mov_b32_e32 v6, v240
	v_mov_b32_e32 v7, v241
	v_mov_b32_e32 v8, v242
	v_mov_b32_e32 v9, v243
	v_mov_b32_e32 v10, v244
	v_mov_b32_e32 v11, v245
	v_mov_b32_e32 v12, v246
	v_mov_b32_e32 v13, v247
	v_mov_b32_e32 v14, v248
	v_mov_b32_e32 v15, v249
	v_mov_b32_e32 v98, v250
	v_mov_b32_e32 v99, v251
	v_mov_b32_e32 v100, v252
	v_mov_b32_e32 v101, v253
	v_bfe_u32 v28, s57, v18, 8
	v_lshl_add_u32 v218, s99, 6, v28
	v_mad_u32_u24 v21, v28, s82, v19
	v_mad_u32_u24 v32, v28, s82, v31
	v_and_b32_e32 v29, s18, v230
	v_cmp_ne_u32_e64 s[54:55], 0, v29
	s_and_b64 s[54:55], s[54:55], s[6:7]
	s_add_i32 s69, s68, 1
	s_min_u32 s14, s69, 63
	s_nop 3
	v_readlane_b32 s30, v26, s14
	v_readlane_b32 s31, v27, s14
	v_bfe_u32 v28, s31, v18, 8
	v_lshl_add_u32 v29, s99, 6, v28
	v_mad_u32_u24 v29, v29, s47, v20
	global_load_dwordx4 v[238:241], v29, s[20:21]
	global_load_dwordx4 v[242:245], v29, s[20:21] offset:32
	global_load_dwordx4 v[246:249], v29, s[20:21] offset:64
	global_load_dwordx4 v[250:253], v29, s[20:21] offset:96
	s_lshl_b32 s0, s100, 6
	v_or_b32_e32 v237, s0, v206
	v_mov_b32_e32 v221, 0
	s_cmp_lg_u32 s100, s99
	s_cbranch_scc1 .Lq_s0n_k2
	v_and_b32_e32 v82, s18, v230
	v_cmp_ne_u32_e32 vcc, 0, v82
	s_and_b64 vcc, s[6:7], vcc
	v_mov_b32 v83, 0
	v_or_b32_e32 v16, 2, v237
	v_cndmask_b32_e32 v82, v236, v222, vcc
	v_sub_f32_e32 v82, v83, v82
	v_mov_b32_e32 v83, v82
	v_mov_b32_e32 v84, v82
	v_mov_b32_e32 v85, v82
	v_mov_b32_e32 v86, v82
	v_mov_b32_e32 v87, v82
	v_mov_b32_e32 v88, v82
	v_mov_b32_e32 v89, v82
	v_mov_b32_e32 v90, v82
	v_mov_b32_e32 v91, v82
	v_mov_b32_e32 v92, v82
	v_mov_b32_e32 v93, v82
	v_mov_b32_e32 v94, v82
	v_mov_b32_e32 v95, v82
	v_mov_b32_e32 v96, v82
	v_mov_b32_e32 v97, v82
	v_cmp_le_i32_e32 vcc, v237, v218
	v_or_b32_e32 v17, 3, v237
	v_mfma_f32_32x32x16_bf16 v[82:97], v[162:165], v[4:7], v[82:97]
	v_or_b32_e32 v30, 8, v237
	v_mfma_f32_32x32x16_bf16 v[82:97], v[154:157], v[8:11], v[82:97]
	v_mfma_f32_32x32x16_bf16 v[82:97], v[150:153], v[12:15], v[82:97]
	v_mfma_f32_32x32x16_bf16 v[82:97], v[158:161], v[98:101], v[82:97]
	s_nop 11
	v_exp_f32_e32 v82, v82
	v_exp_f32_e32 v83, v83
	v_exp_f32_e32 v84, v84
	v_exp_f32_e32 v85, v85
	v_exp_f32_e32 v86, v86
	v_cndmask_b32_e32 v82, 0, v82, vcc
	v_cmp_lt_i32_e32 vcc, v237, v218
	v_exp_f32_e32 v87, v87
	v_exp_f32_e32 v88, v88
	v_cndmask_b32_e32 v83, 0, v83, vcc
	v_cmp_le_i32_e32 vcc, v16, v218
	v_or_b32_e32 v16, 9, v237
	v_exp_f32_e32 v89, v89
	v_cndmask_b32_e32 v84, 0, v84, vcc
	v_cmp_le_i32_e32 vcc, v17, v218
	v_exp_f32_e32 v90, v90
	v_exp_f32_e32 v91, v91
	v_cndmask_b32_e32 v85, 0, v85, vcc
	v_cmp_le_i32_e32 vcc, v30, v218
	v_add_f32_e32 v221, v221, v82
	v_exp_f32_e32 v92, v92
	v_cndmask_b32_e32 v86, 0, v86, vcc
	v_cmp_le_i32_e32 vcc, v16, v218
	v_or_b32_e32 v16, 10, v237
	v_add_f32_e32 v221, v83, v221
	v_cndmask_b32_e32 v87, 0, v87, vcc
	v_cmp_le_i32_e32 vcc, v16, v218
	v_or_b32_e32 v16, 11, v237
	v_exp_f32_e32 v93, v93
	v_cndmask_b32_e32 v88, 0, v88, vcc
	v_cmp_le_i32_e32 vcc, v16, v218
	v_or_b32_e32 v16, 16, v237
	v_add_f32_e32 v221, v84, v221
	v_cndmask_b32_e32 v89, 0, v89, vcc
	v_cmp_le_i32_e32 vcc, v16, v218
	v_or_b32_e32 v16, 17, v237
	v_exp_f32_e32 v94, v94
	v_cndmask_b32_e32 v90, 0, v90, vcc
	v_cmp_le_i32_e32 vcc, v16, v218
	v_or_b32_e32 v16, 18, v237
	v_add_f32_e32 v221, v85, v221
	v_cndmask_b32_e32 v91, 0, v91, vcc
	v_cmp_le_i32_e32 vcc, v16, v218
	v_or_b32_e32 v16, 19, v237
	v_exp_f32_e32 v95, v95
	v_add_f32_e32 v221, v86, v221
	v_cndmask_b32_e32 v92, 0, v92, vcc
	v_cmp_le_i32_e32 vcc, v16, v218
	v_or_b32_e32 v16, 24, v237
	v_cvt_pk_bf16_f32 v82, v82, v83
	v_cvt_pk_bf16_f32 v83, v84, v85
	v_cvt_pk_bf16_f32 v84, v86, v87
	v_cvt_pk_bf16_f32 v85, v88, v89
	v_add_f32_e32 v221, v87, v221
	v_cndmask_b32_e32 v93, 0, v93, vcc
	v_cmp_le_i32_e32 vcc, v16, v218
	v_or_b32_e32 v16, 25, v237
	v_mfma_f32_32x32x16_bf16 v[66:81], v[138:141], v[82:85], 0
	v_add_f32_e32 v221, v88, v221
	v_cndmask_b32_e32 v94, 0, v94, vcc
	v_exp_f32_e32 v86, v96
	v_cmp_le_i32_e32 vcc, v16, v218
	v_or_b32_e32 v88, 26, v237
	v_add_f32_e32 v221, v89, v221
	v_cndmask_b32_e32 v87, 0, v95, vcc
	v_mfma_f32_32x32x16_bf16 v[50:65], v[122:125], v[82:85], 0
	v_cmp_le_i32_e32 vcc, v88, v218
	v_exp_f32_e32 v88, v97
	v_or_b32_e32 v82, 27, v237
	v_cndmask_b32_e32 v86, 0, v86, vcc
	v_cmp_le_i32_e32 vcc, v82, v218
	v_cvt_pk_bf16_f32 v82, v90, v91
	v_cvt_pk_bf16_f32 v83, v92, v93
	v_cndmask_b32_e32 v88, 0, v88, vcc
	v_cvt_pk_bf16_f32 v84, v94, v87
	v_cvt_pk_bf16_f32 v85, v86, v88
	v_add_f32_e32 v221, v90, v221
	v_add_f32_e32 v89, v91, v221
	v_mfma_f32_32x32x16_bf16 v[66:81], v[110:113], v[82:85], v[66:81]
	v_add_f32_e32 v89, v92, v89
	v_add_f32_e32 v89, v93, v89
	v_add_f32_e32 v89, v94, v89
	v_add_f32_e32 v87, v87, v89
	v_add_f32_e32 v86, v86, v87
	v_add_f32_e32 v221, v88, v86
	v_mfma_f32_32x32x16_bf16 v[50:65], v[106:109], v[82:85], v[50:65]
	s_branch .Lq_s0d_k2
.Lq_s0n_k2:
	v_and_b32_e32 v82, s18, v230
	v_cmp_ne_u32_e32 vcc, 0, v82
	s_and_b64 vcc, s[6:7], vcc
	v_mov_b32 v83, 0
	v_cndmask_b32_e32 v82, v236, v222, vcc
	v_sub_f32_e32 v82, v83, v82
	v_mov_b32_e32 v83, v82
	v_mov_b32_e32 v84, v82
	v_mov_b32_e32 v85, v82
	v_mov_b32_e32 v86, v82
	v_mov_b32_e32 v87, v82
	v_mov_b32_e32 v88, v82
	v_mov_b32_e32 v89, v82
	v_mov_b32_e32 v90, v82
	v_mov_b32_e32 v91, v82
	v_mov_b32_e32 v92, v82
	v_mov_b32_e32 v93, v82
	v_mov_b32_e32 v94, v82
	v_mov_b32_e32 v95, v82
	v_mov_b32_e32 v96, v82
	v_mov_b32_e32 v97, v82
	s_nop 0
	s_nop 0
	v_mfma_f32_32x32x16_bf16 v[82:97], v[162:165], v[4:7], v[82:97]
	v_mfma_f32_32x32x16_bf16 v[82:97], v[154:157], v[8:11], v[82:97]
	v_mfma_f32_32x32x16_bf16 v[82:97], v[150:153], v[12:15], v[82:97]
	v_mfma_f32_32x32x16_bf16 v[82:97], v[158:161], v[98:101], v[82:97]
	s_nop 11
	v_exp_f32_e32 v82, v82
	v_exp_f32_e32 v83, v83
	v_exp_f32_e32 v84, v84
	v_exp_f32_e32 v85, v85
	v_exp_f32_e32 v86, v86
	v_exp_f32_e32 v87, v87
	v_exp_f32_e32 v88, v88
	v_exp_f32_e32 v89, v89
	v_exp_f32_e32 v90, v90
	v_exp_f32_e32 v91, v91
	v_add_f32_e32 v221, v221, v82
	v_exp_f32_e32 v92, v92
	v_add_f32_e32 v221, v83, v221
	v_exp_f32_e32 v93, v93
	v_add_f32_e32 v221, v84, v221
	v_exp_f32_e32 v94, v94
	v_add_f32_e32 v221, v85, v221
	v_exp_f32_e32 v95, v95
	v_add_f32_e32 v221, v86, v221
	v_cvt_pk_bf16_f32 v82, v82, v83
	v_cvt_pk_bf16_f32 v83, v84, v85
	v_cvt_pk_bf16_f32 v84, v86, v87
	v_cvt_pk_bf16_f32 v85, v88, v89
	v_add_f32_e32 v221, v87, v221
	s_nop 0
	v_mfma_f32_32x32x16_bf16 v[66:81], v[138:141], v[82:85], 0
	v_add_f32_e32 v221, v88, v221
	v_exp_f32_e32 v86, v96
	v_add_f32_e32 v221, v89, v221
	v_mov_b32_e32 v87, v95
	v_mfma_f32_32x32x16_bf16 v[50:65], v[122:125], v[82:85], 0
	v_exp_f32_e32 v88, v97
	v_cvt_pk_bf16_f32 v82, v90, v91
	v_cvt_pk_bf16_f32 v83, v92, v93
	v_cvt_pk_bf16_f32 v84, v94, v87
	v_cvt_pk_bf16_f32 v85, v86, v88
	v_add_f32_e32 v221, v90, v221
	v_add_f32_e32 v89, v91, v221
	v_mfma_f32_32x32x16_bf16 v[66:81], v[110:113], v[82:85], v[66:81]
	v_add_f32_e32 v89, v92, v89
	v_add_f32_e32 v89, v93, v89
	v_add_f32_e32 v89, v94, v89
	v_add_f32_e32 v87, v87, v89
	v_add_f32_e32 v86, v86, v87
	v_add_f32_e32 v221, v88, v86
	v_mfma_f32_32x32x16_bf16 v[50:65], v[106:109], v[82:85], v[50:65]
.Lq_s0d_k2:
	s_lshl_b32 s69, s68, 1
	s_add_i32 s69, s69, 3
	s_lshr_b32 s15, s69, 1
	s_min_u32 s14, s15, 63
	s_nop 3
	v_readlane_b32 s30, v26, s14
	v_readlane_b32 s31, v27, s14
	s_and_b32 s30, s30, 0xff
	s_lshl_b32 s30, s30, 13
	s_and_b32 s31, s69, 1
	s_lshl_b32 s31, s31, 12
	s_or_b32 s30, s30, s31
	s_add_u32 s64, s11, s30
	s_addc_u32 s65, s12, 0
	s_add_u32 s66, s8, s30
	s_addc_u32 s67, s9, 0
	global_load_dwordx4 v[162:165], v2, s[64:65]
	global_load_dwordx4 v[154:157], v2, s[64:65] offset:1024
	global_load_dwordx4 v[150:153], v2, s[64:65] offset:2048
	global_load_dwordx4 v[158:161], v2, s[64:65] offset:3072
	global_load_dwordx4 v[138:141], v2, s[66:67]
	global_load_dwordx4 v[122:125], v2, s[66:67] offset:1024
	global_load_dwordx4 v[110:113], v2, s[66:67] offset:2048
	global_load_dwordx4 v[106:109], v2, s[66:67] offset:3072
	s_waitcnt vmcnt(20)
	s_lshl_b32 s0, s100, 6
	s_or_b32 s0, s0, 32
	v_or_b32_e32 v237, s0, v206
	s_cmp_lg_u32 s100, s99
	s_cbranch_scc1 .Lq_s1n_k2
	v_and_b32_e32 v82, s18, v230
	v_cmp_ne_u32_e32 vcc, 0, v82
	s_and_b64 vcc, s[6:7], vcc
	v_mov_b32 v83, 0
	v_or_b32_e32 v16, 2, v237
	v_cndmask_b32_e32 v82, v236, v222, vcc
	v_sub_f32_e32 v82, v83, v82
	v_mov_b32_e32 v83, v82
	v_mov_b32_e32 v84, v82
	v_mov_b32_e32 v85, v82
	v_mov_b32_e32 v86, v82
	v_mov_b32_e32 v87, v82
	v_mov_b32_e32 v88, v82
	v_mov_b32_e32 v89, v82
	v_mov_b32_e32 v90, v82
	v_mov_b32_e32 v91, v82
	v_mov_b32_e32 v92, v82
	v_mov_b32_e32 v93, v82
	v_mov_b32_e32 v94, v82
	v_mov_b32_e32 v95, v82
	v_mov_b32_e32 v96, v82
	v_mov_b32_e32 v97, v82
	v_cmp_le_i32_e32 vcc, v237, v218
	v_or_b32_e32 v17, 3, v237
	v_mfma_f32_32x32x16_bf16 v[82:97], v[194:197], v[4:7], v[82:97]
	v_or_b32_e32 v30, 8, v237
	v_mfma_f32_32x32x16_bf16 v[82:97], v[190:193], v[8:11], v[82:97]
	v_mfma_f32_32x32x16_bf16 v[82:97], v[186:189], v[12:15], v[82:97]
	v_mfma_f32_32x32x16_bf16 v[82:97], v[182:185], v[98:101], v[82:97]
	s_nop 11
	v_exp_f32_e32 v82, v82
	v_exp_f32_e32 v83, v83
	v_exp_f32_e32 v84, v84
	v_exp_f32_e32 v85, v85
	v_exp_f32_e32 v86, v86
	v_cndmask_b32_e32 v82, 0, v82, vcc
	v_cmp_lt_i32_e32 vcc, v237, v218
	v_exp_f32_e32 v87, v87
	v_exp_f32_e32 v88, v88
	v_cndmask_b32_e32 v83, 0, v83, vcc
	v_cmp_le_i32_e32 vcc, v16, v218
	v_or_b32_e32 v16, 9, v237
	v_exp_f32_e32 v89, v89
	v_cndmask_b32_e32 v84, 0, v84, vcc
	v_cmp_le_i32_e32 vcc, v17, v218
	v_exp_f32_e32 v90, v90
	v_exp_f32_e32 v91, v91
	v_cndmask_b32_e32 v85, 0, v85, vcc
	v_cmp_le_i32_e32 vcc, v30, v218
	v_add_f32_e32 v221, v221, v82
	v_exp_f32_e32 v92, v92
	v_cndmask_b32_e32 v86, 0, v86, vcc
	v_cmp_le_i32_e32 vcc, v16, v218
	v_or_b32_e32 v16, 10, v237
	v_add_f32_e32 v221, v83, v221
	v_cndmask_b32_e32 v87, 0, v87, vcc
	v_cmp_le_i32_e32 vcc, v16, v218
	v_or_b32_e32 v16, 11, v237
	v_exp_f32_e32 v93, v93
	v_cndmask_b32_e32 v88, 0, v88, vcc
	v_cmp_le_i32_e32 vcc, v16, v218
	v_or_b32_e32 v16, 16, v237
	v_add_f32_e32 v221, v84, v221
	v_cndmask_b32_e32 v89, 0, v89, vcc
	v_cmp_le_i32_e32 vcc, v16, v218
	v_or_b32_e32 v16, 17, v237
	v_exp_f32_e32 v94, v94
	v_cndmask_b32_e32 v90, 0, v90, vcc
	v_cmp_le_i32_e32 vcc, v16, v218
	v_or_b32_e32 v16, 18, v237
	v_add_f32_e32 v221, v85, v221
	v_cndmask_b32_e32 v91, 0, v91, vcc
	v_cmp_le_i32_e32 vcc, v16, v218
	v_or_b32_e32 v16, 19, v237
	v_exp_f32_e32 v95, v95
	v_add_f32_e32 v221, v86, v221
	v_cndmask_b32_e32 v92, 0, v92, vcc
	v_cmp_le_i32_e32 vcc, v16, v218
	v_or_b32_e32 v16, 24, v237
	v_cvt_pk_bf16_f32 v82, v82, v83
	v_cvt_pk_bf16_f32 v83, v84, v85
	v_cvt_pk_bf16_f32 v84, v86, v87
	v_cvt_pk_bf16_f32 v85, v88, v89
	v_add_f32_e32 v221, v87, v221
	v_cndmask_b32_e32 v93, 0, v93, vcc
	v_cmp_le_i32_e32 vcc, v16, v218
	v_or_b32_e32 v16, 25, v237
	v_mfma_f32_32x32x16_bf16 v[66:81], v[134:137], v[82:85], v[66:81]
	v_add_f32_e32 v221, v88, v221
	v_cndmask_b32_e32 v94, 0, v94, vcc
	v_exp_f32_e32 v86, v96
	v_cmp_le_i32_e32 vcc, v16, v218
	v_or_b32_e32 v88, 26, v237
	v_add_f32_e32 v221, v89, v221
	v_cndmask_b32_e32 v87, 0, v95, vcc
	v_mfma_f32_32x32x16_bf16 v[50:65], v[130:133], v[82:85], v[50:65]
	v_cmp_le_i32_e32 vcc, v88, v218
	v_exp_f32_e32 v88, v97
	v_or_b32_e32 v82, 27, v237
	v_cndmask_b32_e32 v86, 0, v86, vcc
	v_cmp_le_i32_e32 vcc, v82, v218
	v_cvt_pk_bf16_f32 v82, v90, v91
	v_cvt_pk_bf16_f32 v83, v92, v93
	v_cndmask_b32_e32 v88, 0, v88, vcc
	v_cvt_pk_bf16_f32 v84, v94, v87
	v_cvt_pk_bf16_f32 v85, v86, v88
	v_add_f32_e32 v221, v90, v221
	v_add_f32_e32 v89, v91, v221
	v_mfma_f32_32x32x16_bf16 v[66:81], v[118:121], v[82:85], v[66:81]
	v_add_f32_e32 v89, v92, v89
	v_add_f32_e32 v89, v93, v89
	v_add_f32_e32 v89, v94, v89
	v_add_f32_e32 v87, v87, v89
	v_add_f32_e32 v86, v86, v87
	v_add_f32_e32 v221, v88, v86
	v_mfma_f32_32x32x16_bf16 v[50:65], v[102:105], v[82:85], v[50:65]
	s_branch .Lq_s1d_k2
.Lq_s1n_k2:
	v_and_b32_e32 v82, s18, v230
	v_cmp_ne_u32_e32 vcc, 0, v82
	s_and_b64 vcc, s[6:7], vcc
	v_mov_b32 v83, 0
	v_cndmask_b32_e32 v82, v236, v222, vcc
	v_sub_f32_e32 v82, v83, v82
	v_mov_b32_e32 v83, v82
	v_mov_b32_e32 v84, v82
	v_mov_b32_e32 v85, v82
	v_mov_b32_e32 v86, v82
	v_mov_b32_e32 v87, v82
	v_mov_b32_e32 v88, v82
	v_mov_b32_e32 v89, v82
	v_mov_b32_e32 v90, v82
	v_mov_b32_e32 v91, v82
	v_mov_b32_e32 v92, v82
	v_mov_b32_e32 v93, v82
	v_mov_b32_e32 v94, v82
	v_mov_b32_e32 v95, v82
	v_mov_b32_e32 v96, v82
	v_mov_b32_e32 v97, v82
	s_nop 0
	s_nop 0
	v_mfma_f32_32x32x16_bf16 v[82:97], v[194:197], v[4:7], v[82:97]
	v_mfma_f32_32x32x16_bf16 v[82:97], v[190:193], v[8:11], v[82:97]
	v_mfma_f32_32x32x16_bf16 v[82:97], v[186:189], v[12:15], v[82:97]
	v_mfma_f32_32x32x16_bf16 v[82:97], v[182:185], v[98:101], v[82:97]
	s_nop 11
	v_exp_f32_e32 v82, v82
	v_exp_f32_e32 v83, v83
	v_exp_f32_e32 v84, v84
	v_exp_f32_e32 v85, v85
	v_exp_f32_e32 v86, v86
	v_exp_f32_e32 v87, v87
	v_exp_f32_e32 v88, v88
	v_exp_f32_e32 v89, v89
	v_exp_f32_e32 v90, v90
	v_exp_f32_e32 v91, v91
	v_add_f32_e32 v221, v221, v82
	v_exp_f32_e32 v92, v92
	v_add_f32_e32 v221, v83, v221
	v_exp_f32_e32 v93, v93
	v_add_f32_e32 v221, v84, v221
	v_exp_f32_e32 v94, v94
	v_add_f32_e32 v221, v85, v221
	v_exp_f32_e32 v95, v95
	v_add_f32_e32 v221, v86, v221
	v_cvt_pk_bf16_f32 v82, v82, v83
	v_cvt_pk_bf16_f32 v83, v84, v85
	v_cvt_pk_bf16_f32 v84, v86, v87
	v_cvt_pk_bf16_f32 v85, v88, v89
	v_add_f32_e32 v221, v87, v221
	s_nop 0
	v_mfma_f32_32x32x16_bf16 v[66:81], v[134:137], v[82:85], v[66:81]
	v_add_f32_e32 v221, v88, v221
	v_exp_f32_e32 v86, v96
	v_add_f32_e32 v221, v89, v221
	v_mov_b32_e32 v87, v95
	v_mfma_f32_32x32x16_bf16 v[50:65], v[130:133], v[82:85], v[50:65]
	v_exp_f32_e32 v88, v97
	v_cvt_pk_bf16_f32 v82, v90, v91
	v_cvt_pk_bf16_f32 v83, v92, v93
	v_cvt_pk_bf16_f32 v84, v94, v87
	v_cvt_pk_bf16_f32 v85, v86, v88
	v_add_f32_e32 v221, v90, v221
	v_add_f32_e32 v89, v91, v221
	v_mfma_f32_32x32x16_bf16 v[66:81], v[118:121], v[82:85], v[66:81]
	v_add_f32_e32 v89, v92, v89
	v_add_f32_e32 v89, v93, v89
	v_add_f32_e32 v89, v94, v89
	v_add_f32_e32 v87, v87, v89
	v_add_f32_e32 v86, v86, v87
	v_add_f32_e32 v221, v88, v86
	v_mfma_f32_32x32x16_bf16 v[50:65], v[102:105], v[82:85], v[50:65]
.Lq_s1d_k2:
	s_lshl_b32 s69, s68, 1
	s_add_i32 s69, s69, 4
	s_lshr_b32 s15, s69, 1
	s_min_u32 s14, s15, 63
	s_nop 3
	v_readlane_b32 s30, v26, s14
	v_readlane_b32 s31, v27, s14
	s_and_b32 s30, s30, 0xff
	s_lshl_b32 s30, s30, 13
	s_and_b32 s31, s69, 1
	s_lshl_b32 s31, s31, 12
	s_or_b32 s30, s30, s31
	s_add_u32 s64, s11, s30
	s_addc_u32 s65, s12, 0
	s_add_u32 s66, s8, s30
	s_addc_u32 s67, s9, 0
	global_load_dwordx4 v[194:197], v2, s[64:65]
	global_load_dwordx4 v[190:193], v2, s[64:65] offset:1024
	global_load_dwordx4 v[186:189], v2, s[64:65] offset:2048
	global_load_dwordx4 v[182:185], v2, s[64:65] offset:3072
	global_load_dwordx4 v[134:137], v2, s[66:67]
	global_load_dwordx4 v[130:133], v2, s[66:67] offset:1024
	global_load_dwordx4 v[118:121], v2, s[66:67] offset:2048
	global_load_dwordx4 v[102:105], v2, s[66:67] offset:3072
	s_mov_b64 s[60:61], 0
	s_lshr_b32 s0, s56, 8
	s_cmp_gt_u32 s0, 0
	s_cbranch_scc0 .Lq_m0_k2
	s_bfe_u32 s1, s57, 0x80000
	s_bitset1_b64 s[60:61], s1

.Lq_locked_k2:
	s_mov_b64 exec, s[54:55]
	ds_read_b128 v[82:85], v21
	ds_read_b128 v[86:89], v21 offset:32
	ds_read_b128 v[90:93], v21 offset:64
	ds_read_b128 v[94:97], v21 offset:96
	ds_read_b128 v[34:37], v21 offset:128
	ds_read_b128 v[38:41], v21 offset:160
	ds_read_b128 v[42:45], v21 offset:192
	ds_read_b128 v[46:49], v21 offset:224
	ds_read_b32 v28, v32
	s_waitcnt lgkmcnt(0)
	v_add_f32_e32 v82, v82, v66
	v_add_f32_e32 v83, v83, v67
	v_add_f32_e32 v84, v84, v68
	v_add_f32_e32 v85, v85, v69
	v_add_f32_e32 v86, v86, v70
	v_add_f32_e32 v87, v87, v71
	v_add_f32_e32 v88, v88, v72
	v_add_f32_e32 v89, v89, v73
	v_add_f32_e32 v90, v90, v74
	v_add_f32_e32 v91, v91, v75
	v_add_f32_e32 v92, v92, v76
	v_add_f32_e32 v93, v93, v77
	v_add_f32_e32 v94, v94, v78
	v_add_f32_e32 v95, v95, v79
	v_add_f32_e32 v96, v96, v80
	v_add_f32_e32 v97, v97, v81
	v_add_f32_e32 v34, v34, v50
	v_add_f32_e32 v35, v35, v51
	v_add_f32_e32 v36, v36, v52
	v_add_f32_e32 v37, v37, v53
	v_add_f32_e32 v38, v38, v54
	v_add_f32_e32 v39, v39, v55
	v_add_f32_e32 v40, v40, v56
	v_add_f32_e32 v41, v41, v57
	v_add_f32_e32 v42, v42, v58
	v_add_f32_e32 v43, v43, v59
	v_add_f32_e32 v44, v44, v60
	v_add_f32_e32 v45, v45, v61
	v_add_f32_e32 v46, v46, v62
	v_add_f32_e32 v47, v47, v63
	v_add_f32_e32 v48, v48, v64
	v_add_f32_e32 v49, v49, v65
	v_add_f32_e32 v28, v28, v221
	ds_write_b128 v21, v[82:85]
	ds_write_b128 v21, v[86:89] offset:32
	ds_write_b128 v21, v[90:93] offset:64
	ds_write_b128 v21, v[94:97] offset:96
	ds_write_b128 v21, v[34:37] offset:128
	ds_write_b128 v21, v[38:41] offset:160
	ds_write_b128 v21, v[42:45] offset:192
	ds_write_b128 v21, v[46:49] offset:224
	ds_write_b32 v32, v28
	s_mov_b64 exec, 1
	s_not_b64 s[64:65], s[60:61]
	v_mov_b32_e32 v16, s64
	v_mov_b32_e32 v17, s65
	ds_and_b64 v33, v[16:17]
	s_mov_b64 exec, s[58:59]
	s_add_i32 s52, s52, 6
	s_branch .Lq_loop
.Lq_loop_end:
	s_waitcnt vmcnt(0) lgkmcnt(0)
	s_barrier
	v_mov_b32_e32 v82, v22
	v_mov_b32_e32 v83, v23
	v_mov_b32_e32 v84, v24
	v_mov_b32_e32 v85, v25
	v_mad_u32_u24 v86, v226, s82, v19
	v_add_u32_e32 v87, 0x1980, v86
	v_mad_u32_u24 v88, v226, s82, v31
	v_add_u32_e32 v89, 0x1980, v88
	ds_read_b32 v66, v86
	ds_read_b32 v67, v86 offset:4
	ds_read_b32 v68, v86 offset:8
	ds_read_b32 v69, v86 offset:12
	ds_read_b32 v70, v86 offset:32
	ds_read_b32 v71, v86 offset:36
	ds_read_b32 v72, v86 offset:40
	ds_read_b32 v73, v86 offset:44
	ds_read_b32 v74, v86 offset:64
	ds_read_b32 v75, v86 offset:68
	ds_read_b32 v76, v86 offset:72
	ds_read_b32 v77, v86 offset:76
	ds_read_b32 v78, v86 offset:96
	ds_read_b32 v79, v86 offset:100
	ds_read_b32 v80, v86 offset:104
	ds_read_b32 v81, v86 offset:108
	ds_read_b32 v50, v86 offset:128
	ds_read_b32 v51, v86 offset:132
	ds_read_b32 v52, v86 offset:136
	ds_read_b32 v53, v86 offset:140
	ds_read_b32 v54, v86 offset:160
	ds_read_b32 v55, v86 offset:164
	ds_read_b32 v56, v86 offset:168
	ds_read_b32 v57, v86 offset:172
	ds_read_b32 v58, v86 offset:192
	ds_read_b32 v59, v86 offset:196
	ds_read_b32 v60, v86 offset:200
	ds_read_b32 v61, v86 offset:204
	ds_read_b32 v62, v86 offset:224
	ds_read_b32 v63, v86 offset:228
	ds_read_b32 v64, v86 offset:232
	ds_read_b32 v65, v86 offset:236
	ds_read_b32 v221, v88
	ds_read_b32 v34, v87
	ds_read_b32 v35, v87 offset:4
	ds_read_b32 v36, v87 offset:8
	ds_read_b32 v37, v87 offset:12
	ds_read_b32 v38, v87 offset:32
	ds_read_b32 v39, v87 offset:36
	ds_read_b32 v40, v87 offset:40
	ds_read_b32 v41, v87 offset:44
	ds_read_b32 v42, v87 offset:64
	ds_read_b32 v43, v87 offset:68
	ds_read_b32 v44, v87 offset:72
	ds_read_b32 v45, v87 offset:76
	ds_read_b32 v46, v87 offset:96
	ds_read_b32 v47, v87 offset:100
	ds_read_b32 v48, v87 offset:104
	ds_read_b32 v49, v87 offset:108
	ds_read_b32 v18, v87 offset:128
	ds_read_b32 v19, v87 offset:132
	ds_read_b32 v20, v87 offset:136
	ds_read_b32 v21, v87 offset:140
	ds_read_b32 v22, v87 offset:160
	ds_read_b32 v23, v87 offset:164
	ds_read_b32 v24, v87 offset:168
	ds_read_b32 v25, v87 offset:172
	ds_read_b32 v26, v87 offset:192
	ds_read_b32 v27, v87 offset:196
	ds_read_b32 v28, v87 offset:200
	ds_read_b32 v29, v87 offset:204
	ds_read_b32 v30, v87 offset:224
	ds_read_b32 v31, v87 offset:228
	ds_read_b32 v32, v87 offset:232
	ds_read_b32 v33, v87 offset:236
	ds_read_b32 v211, v89
	s_waitcnt lgkmcnt(0)
	v_mov_b32_e32 v218, v82
	v_mov_b32_e32 v4, v83
	v_mov_b32_e32 v9, v84
	v_mov_b32_e32 v10, v85

.LBB0_1338:
	s_or_b64 exec, exec, s[8:9]
	v_mad_i64_i32 v[10:11], s[8:9], v218, s50, v[216:217]
	v_or_b32_e32 v10, v10, v206
	v_lshlrev_b64 v[10:11], 1, v[10:11]
	s_waitcnt vmcnt(45)
	v_lshl_add_u64 v[14:15], s[24:25], 0, v[10:11]
	global_load_dwordx2 v[16:17], v[14:15], off
	v_lshl_add_u64 v[12:13], s[70:71], 0, v[10:11]
	global_load_dwordx2 v[82:83], v[12:13], off
	v_lshlrev_b64 v[10:11], 11, v[218:219]
	v_lshl_add_u64 v[10:11], s[44:45], 0, v[10:11]
	v_lshlrev_b32_e32 v2, 1, v206
	v_lshl_add_u64 v[10:11], v[216:217], 1, v[10:11]
	v_lshl_add_u64 v[10:11], v[10:11], 0, v[2:3]
	ds_bpermute_b32 v5, v205, v211
	s_waitcnt lgkmcnt(0)
	v_add_f32_e32 v5, v211, v5
	v_cmp_lt_f32_e32 vcc, 0, v5
	s_waitcnt vmcnt(1)
	v_lshlrev_b32_e32 v84, 16, v16
	v_and_b32_e32 v85, 0xffff0000, v16
	v_lshlrev_b32_e32 v16, 16, v17
	v_and_b32_e32 v17, 0xffff0000, v17
	s_waitcnt vmcnt(0)
	v_lshlrev_b32_e32 v86, 16, v82
	v_and_b32_e32 v87, 0xffff0000, v82
	v_lshlrev_b32_e32 v82, 16, v83
	v_and_b32_e32 v83, 0xffff0000, v83
	v_pk_fma_f32 v[66:67], v[66:67], v[8:9], v[84:85] op_sel_hi:[1,0,1]
	v_pk_fma_f32 v[16:17], v[68:69], v[8:9], v[16:17] op_sel_hi:[1,0,1]
	v_pk_add_f32 v[66:67], v[66:67], v[86:87]
	v_pk_add_f32 v[16:17], v[16:17], v[82:83]
	v_cvt_pk_bf16_f32 v66, v66, v67
	v_cvt_pk_bf16_f32 v67, v16, v17
	global_store_dwordx2 v[10:11], v[66:67], off
	global_load_dwordx2 v[16:17], v[14:15], off offset:64
	s_nop 0
	global_load_dwordx2 v[66:67], v[12:13], off offset:64
	s_waitcnt vmcnt(1)
	v_lshlrev_b32_e32 v68, 16, v16
	v_and_b32_e32 v69, 0xffff0000, v16
	v_lshlrev_b32_e32 v16, 16, v17
	v_and_b32_e32 v17, 0xffff0000, v17
	s_waitcnt vmcnt(0)
	v_lshlrev_b32_e32 v82, 16, v66
	v_and_b32_e32 v83, 0xffff0000, v66
	v_lshlrev_b32_e32 v66, 16, v67
	v_and_b32_e32 v67, 0xffff0000, v67
	v_pk_fma_f32 v[50:51], v[50:51], v[8:9], v[68:69] op_sel_hi:[1,0,1]
	v_pk_fma_f32 v[16:17], v[52:53], v[8:9], v[16:17] op_sel_hi:[1,0,1]
	v_pk_add_f32 v[50:51], v[50:51], v[82:83]
	v_pk_add_f32 v[16:17], v[16:17], v[66:67]
	v_cvt_pk_bf16_f32 v50, v50, v51
	v_cvt_pk_bf16_f32 v51, v16, v17
	global_store_dwordx2 v[10:11], v[50:51], off offset:64
	global_load_dwordx2 v[16:17], v[14:15], off offset:16
	s_nop 0
	global_load_dwordx2 v[50:51], v[12:13], off offset:16
	s_waitcnt vmcnt(1)
	v_lshlrev_b32_e32 v52, 16, v16
	v_and_b32_e32 v53, 0xffff0000, v16
	v_lshlrev_b32_e32 v16, 16, v17
	v_and_b32_e32 v17, 0xffff0000, v17
	s_waitcnt vmcnt(0)
	v_lshlrev_b32_e32 v66, 16, v50
	v_and_b32_e32 v67, 0xffff0000, v50
	v_lshlrev_b32_e32 v50, 16, v51
	v_and_b32_e32 v51, 0xffff0000, v51
	v_pk_fma_f32 v[52:53], v[70:71], v[8:9], v[52:53] op_sel_hi:[1,0,1]
	v_pk_fma_f32 v[16:17], v[72:73], v[8:9], v[16:17] op_sel_hi:[1,0,1]
	s_nop 0
	v_pk_add_f32 v[16:17], v[16:17], v[50:51]
	v_pk_add_f32 v[50:51], v[52:53], v[66:67]
	s_nop 0
	v_cvt_pk_bf16_f32 v50, v50, v51
	v_cvt_pk_bf16_f32 v51, v16, v17
	global_store_dwordx2 v[10:11], v[50:51], off offset:16
	global_load_dwordx2 v[16:17], v[14:15], off offset:80
	s_nop 0
	global_load_dwordx2 v[50:51], v[12:13], off offset:80
	s_waitcnt vmcnt(1)
	v_lshlrev_b32_e32 v52, 16, v16
	v_and_b32_e32 v53, 0xffff0000, v16
	v_lshlrev_b32_e32 v16, 16, v17
	v_and_b32_e32 v17, 0xffff0000, v17
	s_waitcnt vmcnt(0)
	v_lshlrev_b32_e32 v66, 16, v50
	v_and_b32_e32 v67, 0xffff0000, v50
	v_lshlrev_b32_e32 v50, 16, v51
	v_and_b32_e32 v51, 0xffff0000, v51
	v_pk_fma_f32 v[52:53], v[54:55], v[8:9], v[52:53] op_sel_hi:[1,0,1]
	v_pk_fma_f32 v[16:17], v[56:57], v[8:9], v[16:17] op_sel_hi:[1,0,1]
	s_nop 0
	v_pk_add_f32 v[16:17], v[16:17], v[50:51]
	v_pk_add_f32 v[50:51], v[52:53], v[66:67]
	s_nop 0
	v_cvt_pk_bf16_f32 v50, v50, v51
	v_cvt_pk_bf16_f32 v51, v16, v17
	global_store_dwordx2 v[10:11], v[50:51], off offset:80
	global_load_dwordx2 v[16:17], v[14:15], off offset:32
	s_nop 0
	global_load_dwordx2 v[50:51], v[12:13], off offset:32
	s_waitcnt vmcnt(1)
	v_lshlrev_b32_e32 v52, 16, v16
	v_and_b32_e32 v53, 0xffff0000, v16
	v_lshlrev_b32_e32 v16, 16, v17
	v_and_b32_e32 v17, 0xffff0000, v17
	s_waitcnt vmcnt(0)
	v_lshlrev_b32_e32 v54, 16, v50
	v_and_b32_e32 v55, 0xffff0000, v50
	v_lshlrev_b32_e32 v50, 16, v51
	v_and_b32_e32 v51, 0xffff0000, v51
	v_pk_fma_f32 v[52:53], v[74:75], v[8:9], v[52:53] op_sel_hi:[1,0,1]
	v_pk_fma_f32 v[16:17], v[76:77], v[8:9], v[16:17] op_sel_hi:[1,0,1]
	s_nop 0
	v_pk_add_f32 v[16:17], v[16:17], v[50:51]
	v_pk_add_f32 v[50:51], v[52:53], v[54:55]
	s_nop 0
	v_cvt_pk_bf16_f32 v50, v50, v51
	v_cvt_pk_bf16_f32 v51, v16, v17
	global_store_dwordx2 v[10:11], v[50:51], off offset:32
	global_load_dwordx2 v[16:17], v[14:15], off offset:96
	s_nop 0
	global_load_dwordx2 v[50:51], v[12:13], off offset:96
	s_waitcnt vmcnt(1)
	v_lshlrev_b32_e32 v52, 16, v16
	v_and_b32_e32 v53, 0xffff0000, v16
	v_lshlrev_b32_e32 v16, 16, v17
	v_and_b32_e32 v17, 0xffff0000, v17
	s_waitcnt vmcnt(0)
	v_lshlrev_b32_e32 v54, 16, v50
	v_and_b32_e32 v55, 0xffff0000, v50
	v_lshlrev_b32_e32 v50, 16, v51
	v_and_b32_e32 v51, 0xffff0000, v51
	v_pk_fma_f32 v[52:53], v[58:59], v[8:9], v[52:53] op_sel_hi:[1,0,1]
	v_pk_fma_f32 v[16:17], v[60:61], v[8:9], v[16:17] op_sel_hi:[1,0,1]
	s_nop 0
	v_pk_add_f32 v[16:17], v[16:17], v[50:51]
	v_pk_add_f32 v[50:51], v[52:53], v[54:55]
	s_nop 0
	v_cvt_pk_bf16_f32 v50, v50, v51
	v_cvt_pk_bf16_f32 v51, v16, v17
	global_store_dwordx2 v[10:11], v[50:51], off offset:96
	global_load_dwordx2 v[16:17], v[14:15], off offset:48
	s_nop 0
	global_load_dwordx2 v[50:51], v[12:13], off offset:48
	s_waitcnt vmcnt(1)
	v_lshlrev_b32_e32 v52, 16, v16
	v_and_b32_e32 v53, 0xffff0000, v16
	v_lshlrev_b32_e32 v16, 16, v17
	v_and_b32_e32 v17, 0xffff0000, v17
	s_waitcnt vmcnt(0)
	v_lshlrev_b32_e32 v54, 16, v50
	v_and_b32_e32 v55, 0xffff0000, v50
	v_lshlrev_b32_e32 v50, 16, v51
	v_and_b32_e32 v51, 0xffff0000, v51
	v_pk_fma_f32 v[52:53], v[78:79], v[8:9], v[52:53] op_sel_hi:[1,0,1]
	v_pk_fma_f32 v[16:17], v[80:81], v[8:9], v[16:17] op_sel_hi:[1,0,1]
	s_nop 0
	v_pk_add_f32 v[16:17], v[16:17], v[50:51]
	v_pk_add_f32 v[50:51], v[52:53], v[54:55]
	s_nop 0
	v_cvt_pk_bf16_f32 v50, v50, v51
	v_cvt_pk_bf16_f32 v51, v16, v17
	global_store_dwordx2 v[10:11], v[50:51], off offset:48
	global_load_dwordx2 v[14:15], v[14:15], off offset:112
	s_nop 0
	global_load_dwordx2 v[12:13], v[12:13], off offset:112
	s_waitcnt vmcnt(1)
	v_lshlrev_b32_e32 v16, 16, v14
	v_and_b32_e32 v17, 0xffff0000, v14
	v_lshlrev_b32_e32 v14, 16, v15
	v_and_b32_e32 v15, 0xffff0000, v15
	s_waitcnt vmcnt(0)
	v_lshlrev_b32_e32 v50, 16, v12
	v_and_b32_e32 v51, 0xffff0000, v12
	v_lshlrev_b32_e32 v12, 16, v13
	v_and_b32_e32 v13, 0xffff0000, v13
	v_pk_fma_f32 v[16:17], v[62:63], v[8:9], v[16:17] op_sel_hi:[1,0,1]
	v_pk_fma_f32 v[8:9], v[64:65], v[8:9], v[14:15] op_sel_hi:[1,0,1]
	s_nop 0
	v_pk_add_f32 v[8:9], v[8:9], v[12:13]
	v_pk_add_f32 v[12:13], v[16:17], v[50:51]
	s_nop 0
	v_cvt_pk_bf16_f32 v12, v12, v13
	v_cvt_pk_bf16_f32 v13, v8, v9
	global_store_dwordx2 v[10:11], v[12:13], off offset:112
	s_and_saveexec_b64 s[8:9], vcc
	s_cbranch_execz .LBB0_1261
	v_mov_b64_e32 v[8:9], s[22:23]
	v_mad_i64_i32 v[8:9], s[10:11], v214, s49, v[8:9]
	v_lshl_add_u64 v[6:7], v[6:7], 2, v[8:9]
	global_load_dword v4, v[6:7], off
	s_waitcnt vmcnt(0)
	v_div_scale_f32 v6, s[10:11], v5, v5, v4
	v_rcp_f32_e32 v7, v6
	v_div_scale_f32 v8, vcc, v4, v5, v4
	v_fma_f32 v9, -v6, v7, 1.0
	v_fmac_f32_e32 v7, v9, v7
	v_mul_f32_e32 v9, v8, v7
	v_fma_f32 v10, -v6, v9, v8
	v_fmac_f32_e32 v9, v10, v7
	v_fma_f32 v6, -v6, v9, v8
	v_div_fmas_f32 v6, v6, v7, v9
	v_div_fixup_f32 v4, v6, v5, v4
	s_branch .LBB0_1261
.LBB0_1340:
.LBB0_1495:
	s_cmp_gt_i32 s75, 11
	s_cselect_b64 s[0:1], -1, 0
	s_and_b64 s[2:3], s[16:17], s[0:1]
	s_andn2_b64 vcc, exec, s[2:3]
	s_cbranch_vccnz .LBB0_1549
	s_waitcnt vmcnt(0)
	s_waitcnt vmcnt(0) lgkmcnt(0)
	s_barrier
	s_mov_b64 s[2:3], exec
	v_readlane_b32 s4, v254, 5
	v_readlane_b32 s5, v254, 6
	s_and_b64 s[4:5], s[2:3], s[4:5]
	s_mov_b64 exec, s[4:5]
	s_cbranch_execz .LBB0_1548
	s_add_i32 s4, 0, 0x23fc0
	v_mov_b32_e32 v1, s4
	s_waitcnt vmcnt(0) expcnt(0) lgkmcnt(0)
	ds_read_b32 v3, v1
	s_add_i32 s4, 0, 0x23fc4
	v_mov_b32_e32 v1, s4
	ds_read_b32 v1, v1
	s_waitcnt lgkmcnt(1)
	v_cmp_ne_u32_e32 vcc, 0, v3
	s_cbranch_vccnz .LBB0_1512
	v_readlane_b32 s4, v254, 0
	v_readlane_b32 s5, v254, 1
	s_load_dwordx2 s[8:9], s[4:5], 0x4
	s_add_u32 s4, s72, 0x71200
	s_addc_u32 s5, s73, 0
	s_add_u32 s6, s72, 0x71400
	s_addc_u32 s7, s73, 0
	s_waitcnt lgkmcnt(0)
	s_mul_i32 s50, s8, s33
	s_add_u32 s8, s72, 0x71500
	s_mul_i32 s50, s50, s9
	s_addc_u32 s9, s73, 0
	s_add_u32 s10, s72, 0x71600
	s_addc_u32 s11, s73, 0
	s_add_u32 s12, s72, 0x71700
	s_addc_u32 s13, s73, 0
	s_add_u32 s14, s72, 0x71800
	s_addc_u32 s15, s73, 0
	s_add_u32 s16, s72, 0x71900
	s_addc_u32 s17, s73, 0
	s_add_u32 s18, s72, 0x71a00
	s_addc_u32 s19, s73, 0
	s_add_u32 s20, s72, 0x71b00
	s_addc_u32 s21, s73, 0
	s_add_u32 s22, s72, 0x71c00
	s_addc_u32 s23, s73, 0
	s_add_u32 s24, s72, 0x71d00
	s_addc_u32 s25, s73, 0
	s_add_u32 s26, s72, 0x71e00
	s_addc_u32 s27, s73, 0
	s_add_u32 s28, s72, 0x71f00
	s_addc_u32 s29, s73, 0
	s_add_u32 s30, s72, 0x72000
	s_addc_u32 s31, s73, 0
	s_add_u32 s34, s72, 0x72100
	s_addc_u32 s35, s73, 0
	s_add_u32 s36, s72, 0x72200
	s_addc_u32 s37, s73, 0
	s_add_u32 s40, s72, 0x72300
	s_addc_u32 s41, s73, 0
	s_mov_b32 s51, 1
	v_mov_b32_e32 v17, 0
	s_branch .LBB0_1500
